# P7b no longer writes x2 f32 to out; P8 FIN epilogue recomputes x2 from x1, d, ssq_d, g_post_mlp (fewer HBM bytes)
# speedup vs baseline: 1.0065x; 1.0065x over previous
; __device__ __forceinline__ unsigned pk2(float lo, float hi) { return pg8::cvt_pk_bf16(lo, hi); }
; __device__ __forceinline__ float bf_lo(unsigned w) { return __uint_as_float(w << 16); }
; __device__ __forceinline__ float bf_hi(unsigned w) { return __uint_as_float(w & 0xffff0000u); }
; #define INP(i) ((const float*)(const GAS float*)KARG(8 * (i)))
; __global__ void __launch_bounds__(512, 2) fwd(Params P) {
;     ...
;     if (PHASE_MASK & (1 << 9)) {
;         const f32x4* g1 = (const f32x4*)INP(16) + lane;
;         for (int m = gw; m < T_TOK; m += NGW) {
;             const float rsd = __builtin_amdgcn_rsqf(ssq_d[m] * (1.f / DM) + EPS);
;             const u32x2* dr = (const u32x2*)(DN + (size_t)m * DM) + lane;
;             f32x4* orow = (f32x4*)(OUT_P + (size_t)m * DM) + lane; u32x2* o = (u32x2*)(XN + (size_t)m * DM) + lane;
; #pragma unroll
;             for (int j = 0; j < 8; ++j) { const f32x4 xv = __builtin_nontemporal_load(&orow[64 * j]); const u32x2 dw = __builtin_nontemporal_load(&dr[64 * j]); const f32x4 g = g1[64 * j];
;                 f32x4 t; t.x = xv.x + bf_lo(dw.x) * rsd * g.x; t.y = xv.y + bf_hi(dw.x) * rsd * g.y; t.z = xv.z + bf_lo(dw.y) * rsd * g.z; t.w = xv.w + bf_hi(dw.y) * rsd * g.w;
;                 orow[64 * j] = t; u32x2 w; w.x = pk2(t.x, t.y); w.y = pk2(t.z, t.w); o[64 * j] = w; }
;         }
.LBB0_1491:
	s_mov_b64 s[16:17], s[0:1]
	s_load_dwordx2 s[16:17], s[16:17], 0xa8
	s_mov_b64 s[18:19], s[0:1]
	s_mov_b64 s[20:21], s[0:1]
	s_mov_b64 s[22:23], s[0:1]
	s_waitcnt lgkmcnt(0)
	s_add_u32 s16, s16, s12
	s_addc_u32 s17, s17, s13
	global_load_dword v19, v167, s[16:17]
	s_load_dwordx2 s[16:17], s[18:19], 0xa8
	s_load_dwordx2 s[18:19], s[20:21], 0xa0
	global_load_dwordx4 v[20:23], v[0:1], off
	s_waitcnt lgkmcnt(0)
	v_lshl_add_u64 v[28:29], s[16:17], 0, v[10:11]
	global_load_dwordx2 v[30:31], v[28:29], off offset:-3584 nt
	v_lshl_add_u64 v[14:15], s[18:19], 0, v[12:13]
	v_add_co_u32_e32 v32, vcc, s14, v14
	s_load_dwordx2 s[16:17], s[22:23], 0xa8
	s_nop 0
	v_addc_co_u32_e32 v33, vcc, -1, v15, vcc
	global_load_dwordx4 v[24:27], v[32:33], off offset:-3072 nt
	s_add_i32 s80, s80, s82
	s_waitcnt lgkmcnt(0)
	v_lshl_add_u64 v[16:17], s[16:17], 0, v[10:11]
	v_add_co_u32_e32 v16, vcc, s15, v16
	s_add_u32 s12, s12, s6
	s_nop 0
	v_addc_co_u32_e32 v17, vcc, -1, v17, vcc
	s_addc_u32 s13, s13, s7
	s_cmpk_gt_i32 s80, 0x7fff
	v_lshl_add_u64 v[12:13], v[12:13], 0, s[10:11]
	v_lshl_add_u64 v[10:11], v[10:11], 0, s[8:9]
	s_waitcnt vmcnt(3)
	v_fmamk_f32 v19, v19, 0x3a000000, v18
	v_rsq_f32_e32 v34, v19
	s_waitcnt vmcnt(1)
	v_lshlrev_b32_e32 v36, 16, v30
	v_and_b32_e32 v37, 0xffff0000, v30
	v_lshlrev_b32_e32 v30, 16, v31
	v_and_b32_e32 v31, 0xffff0000, v31
	v_pk_mul_f32 v[36:37], v[34:35], v[36:37] op_sel_hi:[0,1]
	v_pk_mul_f32 v[30:31], v[34:35], v[30:31] op_sel_hi:[0,1]
	s_waitcnt vmcnt(0)
	v_pk_fma_f32 v[20:21], v[20:21], v[36:37], v[24:25]
	v_pk_fma_f32 v[22:23], v[22:23], v[30:31], v[26:27]
	s_nop 1
	v_cvt_pk_bf16_f32 v20, v20, v21
	v_cvt_pk_bf16_f32 v21, v22, v23
	global_store_dwordx2 v[16:17], v[20:21], off offset:-3584
	global_load_dwordx2 v[30:31], v[28:29], off offset:-3072 nt
	s_nop 0
	global_load_dwordx4 v[20:23], v[32:33], off offset:-2048 nt
	global_load_dwordx4 v[24:27], v[0:1], off offset:1024
	s_waitcnt vmcnt(2)
	v_lshlrev_b32_e32 v36, 16, v30
	v_and_b32_e32 v37, 0xffff0000, v30
	v_lshlrev_b32_e32 v30, 16, v31
	v_and_b32_e32 v31, 0xffff0000, v31
	v_pk_mul_f32 v[36:37], v[34:35], v[36:37] op_sel_hi:[0,1]
	v_pk_mul_f32 v[30:31], v[34:35], v[30:31] op_sel_hi:[0,1]
	s_waitcnt vmcnt(0)
	v_pk_fma_f32 v[20:21], v[24:25], v[36:37], v[20:21]
	v_pk_fma_f32 v[22:23], v[26:27], v[30:31], v[22:23]
	s_nop 1
	v_cvt_pk_bf16_f32 v20, v20, v21
	v_cvt_pk_bf16_f32 v21, v22, v23
	global_store_dwordx2 v[16:17], v[20:21], off offset:-3072
	global_load_dwordx2 v[30:31], v[28:29], off offset:-2560 nt
	s_nop 0
	global_load_dwordx4 v[20:23], v[32:33], off offset:-1024 nt
	global_load_dwordx4 v[24:27], v[0:1], off offset:2048
	s_waitcnt vmcnt(2)
	v_lshlrev_b32_e32 v36, 16, v30
	v_and_b32_e32 v37, 0xffff0000, v30
	v_lshlrev_b32_e32 v30, 16, v31
	v_and_b32_e32 v31, 0xffff0000, v31
	v_pk_mul_f32 v[36:37], v[34:35], v[36:37] op_sel_hi:[0,1]
	v_pk_mul_f32 v[30:31], v[34:35], v[30:31] op_sel_hi:[0,1]
	s_waitcnt vmcnt(0)
	v_pk_fma_f32 v[20:21], v[24:25], v[36:37], v[20:21]
	v_pk_fma_f32 v[22:23], v[26:27], v[30:31], v[22:23]
	s_nop 1
	v_cvt_pk_bf16_f32 v20, v20, v21
	v_cvt_pk_bf16_f32 v21, v22, v23
	global_store_dwordx2 v[16:17], v[20:21], off offset:-2560
	global_load_dwordx2 v[30:31], v[28:29], off offset:-2048 nt
	s_nop 0
	global_load_dwordx4 v[20:23], v[14:15], off offset:-4096 nt
	global_load_dwordx4 v[24:27], v[0:1], off offset:3072
	s_waitcnt vmcnt(2)
	v_lshlrev_b32_e32 v32, 16, v30
	v_and_b32_e32 v33, 0xffff0000, v30
	v_lshlrev_b32_e32 v30, 16, v31
	v_and_b32_e32 v31, 0xffff0000, v31
	v_pk_mul_f32 v[32:33], v[34:35], v[32:33] op_sel_hi:[0,1]
	v_pk_mul_f32 v[30:31], v[34:35], v[30:31] op_sel_hi:[0,1]
	s_waitcnt vmcnt(0)
	v_pk_fma_f32 v[20:21], v[24:25], v[32:33], v[20:21]
	v_pk_fma_f32 v[22:23], v[26:27], v[30:31], v[22:23]
	s_nop 1
	v_cvt_pk_bf16_f32 v20, v20, v21
	v_cvt_pk_bf16_f32 v21, v22, v23
	global_store_dwordx2 v[16:17], v[20:21], off offset:-2048
	global_load_dwordx2 v[30:31], v[28:29], off offset:-1536 nt
	s_nop 0
	global_load_dwordx4 v[20:23], v[14:15], off offset:-3072 nt
	global_load_dwordx4 v[24:27], v[2:3], off
	s_waitcnt vmcnt(2)
	v_lshlrev_b32_e32 v32, 16, v30
	v_and_b32_e32 v33, 0xffff0000, v30
	v_lshlrev_b32_e32 v30, 16, v31
	v_and_b32_e32 v31, 0xffff0000, v31
	v_pk_mul_f32 v[32:33], v[34:35], v[32:33] op_sel_hi:[0,1]
	v_pk_mul_f32 v[30:31], v[34:35], v[30:31] op_sel_hi:[0,1]
	s_waitcnt vmcnt(0)
	v_pk_fma_f32 v[20:21], v[24:25], v[32:33], v[20:21]
	v_pk_fma_f32 v[22:23], v[26:27], v[30:31], v[22:23]
	s_nop 1
	v_cvt_pk_bf16_f32 v20, v20, v21
	v_cvt_pk_bf16_f32 v21, v22, v23
	global_store_dwordx2 v[16:17], v[20:21], off offset:-1536
	global_load_dwordx2 v[30:31], v[28:29], off offset:-1024 nt
	s_nop 0
	global_load_dwordx4 v[20:23], v[14:15], off offset:-2048 nt
	global_load_dwordx4 v[24:27], v[4:5], off
	s_waitcnt vmcnt(2)
	v_lshlrev_b32_e32 v32, 16, v30
	v_and_b32_e32 v33, 0xffff0000, v30
	v_lshlrev_b32_e32 v30, 16, v31
	v_and_b32_e32 v31, 0xffff0000, v31
	v_pk_mul_f32 v[32:33], v[34:35], v[32:33] op_sel_hi:[0,1]
	v_pk_mul_f32 v[30:31], v[34:35], v[30:31] op_sel_hi:[0,1]
	s_waitcnt vmcnt(0)
	v_pk_fma_f32 v[20:21], v[24:25], v[32:33], v[20:21]
	v_pk_fma_f32 v[22:23], v[26:27], v[30:31], v[22:23]
	s_nop 1
	v_cvt_pk_bf16_f32 v20, v20, v21
	v_cvt_pk_bf16_f32 v21, v22, v23
	global_store_dwordx2 v[16:17], v[20:21], off offset:-1024
	global_load_dwordx2 v[30:31], v[28:29], off offset:-512 nt
	s_nop 0
	global_load_dwordx4 v[20:23], v[14:15], off offset:-1024 nt
	global_load_dwordx4 v[24:27], v[6:7], off
	s_waitcnt vmcnt(2)
	v_lshlrev_b32_e32 v32, 16, v30
	v_and_b32_e32 v33, 0xffff0000, v30
	v_lshlrev_b32_e32 v30, 16, v31
	v_and_b32_e32 v31, 0xffff0000, v31
	v_pk_mul_f32 v[32:33], v[34:35], v[32:33] op_sel_hi:[0,1]
	v_pk_mul_f32 v[30:31], v[34:35], v[30:31] op_sel_hi:[0,1]
	s_waitcnt vmcnt(0)
	v_pk_fma_f32 v[20:21], v[24:25], v[32:33], v[20:21]
	v_pk_fma_f32 v[22:23], v[26:27], v[30:31], v[22:23]
	s_nop 1
	v_cvt_pk_bf16_f32 v20, v20, v21
	v_cvt_pk_bf16_f32 v21, v22, v23
	global_store_dwordx2 v[16:17], v[20:21], off offset:-512
	global_load_dwordx2 v[30:31], v[28:29], off nt
	s_nop 0
	global_load_dwordx4 v[20:23], v[14:15], off nt
	global_load_dwordx4 v[24:27], v[8:9], off
	s_waitcnt vmcnt(2)
	v_lshlrev_b32_e32 v28, 16, v30
	v_and_b32_e32 v29, 0xffff0000, v30
	v_lshlrev_b32_e32 v30, 16, v31
	v_and_b32_e32 v31, 0xffff0000, v31
	v_pk_mul_f32 v[28:29], v[34:35], v[28:29] op_sel_hi:[0,1]
	v_pk_mul_f32 v[30:31], v[34:35], v[30:31] op_sel_hi:[0,1]
	s_waitcnt vmcnt(0)
	v_pk_fma_f32 v[20:21], v[24:25], v[28:29], v[20:21]
	v_pk_fma_f32 v[22:23], v[26:27], v[30:31], v[22:23]
	v_cvt_pk_bf16_f32 v14, v20, v21
	v_cvt_pk_bf16_f32 v15, v22, v23
	global_store_dwordx2 v[16:17], v[14:15], off
	s_cbranch_scc0 .LBB0_1491

; #define INP(i) ((const float*)(const GAS float*)KARG(8 * (i)))
; __global__ void __launch_bounds__(512, 2) fwd(Params P) {
;     ...
;     if (PHASE_MASK & (1 << 10)) {
;         pg8::Gemm g{XN, wb + OFF_WPG, T_TOK, 2048, 2048}; pg8::StaticOrder S; S.init(T_TOK, 2048, G, bx);
;         Epi<EK_FIN> E{}; E.a.g0 = EB; E.a.ssq0 = ssq_e; E.a.outf = OUT_P; E.a.gv = INP(18);
;         pg8::gemm_phase<Epi<EK_FIN>, pg8::StaticOrder, true, true>(lds, g, S, E);
.LBB0_1544:
	s_or_b64 exec, exec, s[6:7]
	s_load_dwordx2 s[86:87], s[0:1], 0x80
	s_load_dwordx2 s[88:89], s[0:1], 0xa8
	s_mov_b64 s[10:11], s[0:1]
	s_mov_b64 s[12:13], s[0:1]
	s_mov_b64 s[6:7], s[0:1]
	s_mov_b64 s[16:17], s[0:1]
	s_mov_b64 s[8:9], s[0:1]
	s_waitcnt lgkmcnt(0)
	s_add_u32 s90, s88, 0x30000000
	s_addc_u32 s91, s89, 0
	s_add_u32 s88, s88, 0x60000
	s_addc_u32 s89, s89, 0
	s_barrier
	s_and_b64 vcc, exec, s[4:5]
	v_readfirstlane_b32 s20, v178
	s_cbranch_vccnz .LBB0_1569
	s_load_dwordx2 s[14:15], s[10:11], 0xa8
	s_load_dwordx2 s[4:5], s[12:13], 0xa8
	s_lshr_b32 s10, s54, 29
	s_add_i32 s23, s84, s10
	s_and_b32 s10, s23, -8
	s_sub_i32 s22, s84, s10
	s_cmp_gt_i32 s22, -1
	s_cbranch_scc0 .LBB0_1547
	s_lshl_b32 s21, s22, 7
	s_mov_b64 s[18:19], 0
	s_branch .LBB0_1548

; __device__ __forceinline__ void load8(const bf16_t* src, float* v) { const u32x4 w = *(const u32x4*)src; v[0] = bf_lo(w.x); v[1] = bf_hi(w.x); v[2] = bf_lo(w.y); v[3] = bf_hi(w.y); v[4] = bf_lo(w.z); v[5] = bf_hi(w.z); v[6] = bf_lo(w.w); v[7] = bf_hi(w.w); }
; __device__ __forceinline__ float sigmoidf_(float v) { return __builtin_amdgcn_rcpf(1.f + __builtin_amdgcn_exp2f(-v * LOG2E)); }
;     __device__ __forceinline__ void operator()(const pg8::f32x4 (&acc)[2][2][4][2], const pg8::Unit& u, int wr, int wc, int fr, int fq) const {
;     ...
;             for (int m = 0; m < 4; ++m) {
;                 const int row = u.pm * 256 + ai * 128 + wr * 64 + m * 16 + fr;
;                 const int bb = row >> 13, ss = row & 8191;
;                 float ssq = 0.f;
;                 float rs = 1.f;
;                 if constexpr (KIND == EK_Q || KIND == EK_KV) rs = __builtin_amdgcn_rsqf(a.ssq0[row] * (1.f / 512.f) + EPS);
;                 if constexpr (KIND == EK_FIN) rs = __builtin_amdgcn_rsqf(a.ssq0[row] * (1.f / 2048.f) + EPS);
; #pragma unroll
;                 for (int bj = 0; bj < 2; ++bj) {
;                     const int cl = bj * 128 + wc * 32 + fq * 8;
;     ...
;                     } else if constexpr (KIND == EK_FIN) {
;                         const int c = pn * 256 + cl; const size_t off = (size_t)row * 2048 + c; float e[8]; load8(a.g0 + off, e);
;                         const f32x4 x0 = *(const f32x4*)(a.outf + off), x1 = *(const f32x4*)(a.outf + off + 4);
;                         const f32x4 g0 = *(const f32x4*)(a.gv + c), g1 = *(const f32x4*)(a.gv + c + 4);
;                         f32x4 r0, r1;
; #pragma unroll
;                         for (int j = 0; j < 4; ++j) { r0[j] = x0[j] + sigmoidf_(v[j]) * (e[j] * rs * g0[j]); r1[j] = x1[j] + sigmoidf_(v[4 + j]) * (e[4 + j] * rs * g1[j]); }
;                         *(f32x4*)(a.outf + off) = r0; *(f32x4*)(a.outf + off + 4) = r1;
.LBB0_1565:
	v_lshl_add_u32 v146, s26, 8, v152
	s_lshl_b32 vcc_lo, s48, 9
	v_lshlrev_b32_e32 v144, 12, v146
	v_lshl_add_u32 v147, v154, 1, vcc_lo
	v_add_u32_e32 v144, v144, v147
	v_lshlrev_b32_e32 v145, 1, v144
	v_lshlrev_b32_e32 v147, 1, v147
	v_lshlrev_b32_e32 v146, 2, v146
	global_load_dword v192, v146, s[12:13]
	global_load_dword v193, v146, s[12:13] offset:64
	global_load_dword v194, v146, s[12:13] offset:128
	global_load_dword v195, v146, s[12:13] offset:192
	global_load_dword v196, v146, s[12:13] offset:512
	global_load_dword v197, v146, s[12:13] offset:576
	global_load_dword v198, v146, s[12:13] offset:640
	global_load_dword v199, v146, s[12:13] offset:704
	global_load_dword v200, v146, s[88:89]
	global_load_dword v201, v146, s[88:89] offset:64
	global_load_dword v202, v146, s[88:89] offset:128
	global_load_dword v203, v146, s[88:89] offset:192
	global_load_dword v204, v146, s[88:89] offset:512
	global_load_dword v205, v146, s[88:89] offset:576
	global_load_dword v206, v146, s[88:89] offset:640
	global_load_dword v207, v146, s[88:89] offset:704
	global_load_dwordx4 v[160:163], v147, s[6:7]
	global_load_dwordx4 v[164:167], v147, s[6:7] offset:16
	global_load_dwordx4 v[168:171], v147, s[6:7] offset:512
	global_load_dwordx4 v[172:175], v147, s[6:7] offset:528
	global_load_dwordx4 v[176:179], v147, s[86:87]
	global_load_dwordx4 v[180:183], v147, s[86:87] offset:16
	global_load_dwordx4 v[184:187], v147, s[86:87] offset:512
	global_load_dwordx4 v[188:191], v147, s[86:87] offset:528
	v_mov_b32_e32 v148, v144
	v_mov_b32_e32 v149, v145
	global_load_dwordx4 v[208:211], v148, s[90:91]
	global_load_dwordx4 v[212:215], v149, s[4:5]
	global_load_dwordx4 v[216:219], v149, s[4:5] offset:16
	global_load_dwordx4 v[220:223], v148, s[10:11]
	global_load_dwordx4 v[224:227], v148, s[90:91] offset:256
	global_load_dwordx4 v[228:231], v149, s[4:5] offset:512
	global_load_dwordx4 v[232:235], v149, s[4:5] offset:528
	global_load_dwordx4 v[236:239], v148, s[10:11] offset:256
	v_mul_f32_e32 v124, 0xbfb8aa3b, v124
	v_mul_f32_e32 v125, 0xbfb8aa3b, v125
	v_mul_f32_e32 v126, 0xbfb8aa3b, v126
	v_mul_f32_e32 v127, 0xbfb8aa3b, v127
	v_mul_f32_e32 v120, 0xbfb8aa3b, v120
	v_mul_f32_e32 v121, 0xbfb8aa3b, v121
	v_mul_f32_e32 v122, 0xbfb8aa3b, v122
	v_mul_f32_e32 v123, 0xbfb8aa3b, v123
	v_exp_f32_e32 v124, v124
	v_exp_f32_e32 v125, v125
	v_exp_f32_e32 v126, v126
	v_exp_f32_e32 v127, v127
	v_exp_f32_e32 v120, v120
	v_exp_f32_e32 v121, v121
	v_exp_f32_e32 v122, v122
	v_exp_f32_e32 v123, v123
	v_add_f32_e32 v124, 1.0, v124
	v_add_f32_e32 v125, 1.0, v125
	v_add_f32_e32 v126, 1.0, v126
	v_add_f32_e32 v127, 1.0, v127
	v_add_f32_e32 v120, 1.0, v120
	v_add_f32_e32 v121, 1.0, v121
	v_add_f32_e32 v122, 1.0, v122
	v_add_f32_e32 v123, 1.0, v123
	v_rcp_f32_e32 v124, v124
	v_rcp_f32_e32 v125, v125
	v_rcp_f32_e32 v126, v126
	v_rcp_f32_e32 v127, v127
	v_rcp_f32_e32 v120, v120
	v_rcp_f32_e32 v121, v121
	v_rcp_f32_e32 v122, v122
	v_rcp_f32_e32 v123, v123
	s_waitcnt vmcnt(4)
	v_fmamk_f32 v192, v192, 0x3a000000, v158
	v_fmamk_f32 v200, v200, 0x3a000000, v158
	v_rsq_f32_e32 v192, v192
	v_rsq_f32_e32 v200, v200
	v_lshlrev_b32_e32 v151, 16, v208
	v_and_b32_e32 v208, 0xffff0000, v208
	v_lshlrev_b32_e32 v159, 16, v209
	v_and_b32_e32 v209, 0xffff0000, v209
	v_lshlrev_b32_e32 v244, 16, v210
	v_and_b32_e32 v210, 0xffff0000, v210
	v_lshlrev_b32_e32 v245, 16, v211
	v_and_b32_e32 v211, 0xffff0000, v211
	v_lshlrev_b32_e32 v240, 16, v220
	v_and_b32_e32 v220, 0xffff0000, v220
	v_lshlrev_b32_e32 v241, 16, v221
	v_and_b32_e32 v221, 0xffff0000, v221
	v_lshlrev_b32_e32 v242, 16, v222
	v_and_b32_e32 v222, 0xffff0000, v222
	v_lshlrev_b32_e32 v243, 16, v223
	v_and_b32_e32 v223, 0xffff0000, v223
	v_mul_f32_e32 v151, v200, v151
	v_mul_f32_e32 v208, v200, v208
	v_mul_f32_e32 v159, v200, v159
	v_mul_f32_e32 v209, v200, v209
	v_mul_f32_e32 v244, v200, v244
	v_mul_f32_e32 v210, v200, v210
	v_mul_f32_e32 v245, v200, v245
	v_mul_f32_e32 v211, v200, v211
	v_mul_f32_e32 v240, v192, v240
	v_mul_f32_e32 v220, v192, v220
	v_mul_f32_e32 v241, v192, v241
	v_mul_f32_e32 v221, v192, v221
	v_mul_f32_e32 v242, v192, v242
	v_mul_f32_e32 v222, v192, v222
	v_mul_f32_e32 v243, v192, v243
	v_mul_f32_e32 v223, v192, v223
	v_fma_f32 v212, v176, v151, v212
	v_fma_f32 v213, v177, v208, v213
	v_fma_f32 v214, v178, v159, v214
	v_fma_f32 v215, v179, v209, v215
	v_fma_f32 v216, v180, v244, v216
	v_fma_f32 v217, v181, v210, v217
	v_fma_f32 v218, v182, v245, v218
	v_fma_f32 v219, v183, v211, v219
	v_mul_f32_e32 v240, v240, v160
	v_mul_f32_e32 v220, v220, v161
	v_mul_f32_e32 v241, v241, v162
	v_mul_f32_e32 v221, v221, v163
	v_mul_f32_e32 v242, v242, v164
	v_mul_f32_e32 v222, v222, v165
	v_mul_f32_e32 v243, v243, v166
	v_mul_f32_e32 v223, v223, v167
	v_fma_f32 v212, v124, v240, v212
	v_fma_f32 v213, v125, v220, v213
	v_fma_f32 v214, v126, v241, v214
	v_fma_f32 v215, v127, v221, v215
	v_fma_f32 v216, v120, v242, v216
	v_fma_f32 v217, v121, v222, v217
	v_fma_f32 v218, v122, v243, v218
	v_fma_f32 v219, v123, v223, v219
	v_mov_b32_e32 v150, v145
	global_store_dwordx4 v150, v[212:215], s[4:5]
	global_store_dwordx4 v150, v[216:219], s[4:5] offset:16
	s_nop 1
	v_add_u32_e32 v148, 0x10000, v144
	v_add_u32_e32 v149, 0x20000, v145
	global_load_dwordx4 v[208:211], v148, s[90:91]
	global_load_dwordx4 v[212:215], v149, s[4:5]
	global_load_dwordx4 v[216:219], v149, s[4:5] offset:16
	global_load_dwordx4 v[220:223], v148, s[10:11]
	v_mul_f32_e32 v116, 0xbfb8aa3b, v116
	v_mul_f32_e32 v117, 0xbfb8aa3b, v117
	v_mul_f32_e32 v118, 0xbfb8aa3b, v118
	v_mul_f32_e32 v119, 0xbfb8aa3b, v119
	v_mul_f32_e32 v112, 0xbfb8aa3b, v112
	v_mul_f32_e32 v113, 0xbfb8aa3b, v113
	v_mul_f32_e32 v114, 0xbfb8aa3b, v114
	v_mul_f32_e32 v115, 0xbfb8aa3b, v115
	v_exp_f32_e32 v116, v116
	v_exp_f32_e32 v117, v117
	v_exp_f32_e32 v118, v118
	v_exp_f32_e32 v119, v119
	v_exp_f32_e32 v112, v112
	v_exp_f32_e32 v113, v113
	v_exp_f32_e32 v114, v114
	v_exp_f32_e32 v115, v115
	v_add_f32_e32 v116, 1.0, v116
	v_add_f32_e32 v117, 1.0, v117
	v_add_f32_e32 v118, 1.0, v118
	v_add_f32_e32 v119, 1.0, v119
	v_add_f32_e32 v112, 1.0, v112
	v_add_f32_e32 v113, 1.0, v113
	v_add_f32_e32 v114, 1.0, v114
	v_add_f32_e32 v115, 1.0, v115
	v_rcp_f32_e32 v116, v116
	v_rcp_f32_e32 v117, v117
	v_rcp_f32_e32 v118, v118
	v_rcp_f32_e32 v119, v119
	v_rcp_f32_e32 v112, v112
	v_rcp_f32_e32 v113, v113
	v_rcp_f32_e32 v114, v114
	v_rcp_f32_e32 v115, v115
	s_waitcnt vmcnt(6)
; __device__ __forceinline__ float bf_lo(unsigned w) { return __uint_as_float(w << 16); }
; __device__ __forceinline__ float bf_hi(unsigned w) { return __uint_as_float(w & 0xffff0000u); }
; __device__ __forceinline__ void load8(const bf16_t* src, float* v) { const u32x4 w = *(const u32x4*)src; v[0] = bf_lo(w.x); v[1] = bf_hi(w.x); v[2] = bf_lo(w.y); v[3] = bf_hi(w.y); v[4] = bf_lo(w.z); v[5] = bf_hi(w.z); v[6] = bf_lo(w.w); v[7] = bf_hi(w.w); }
; __device__ __forceinline__ float sigmoidf_(float v) { return __builtin_amdgcn_rcpf(1.f + __builtin_amdgcn_exp2f(-v * LOG2E)); }
;     __device__ __forceinline__ void operator()(const pg8::f32x4 (&acc)[2][2][4][2], const pg8::Unit& u, int wr, int wc, int fr, int fq) const {
;     ...
;                     } else if constexpr (KIND == EK_FIN) {
;                         const int c = pn * 256 + cl; const size_t off = (size_t)row * 2048 + c; float e[8]; load8(a.g0 + off, e);
;                         const f32x4 x0 = *(const f32x4*)(a.outf + off), x1 = *(const f32x4*)(a.outf + off + 4);
;                         const f32x4 g0 = *(const f32x4*)(a.gv + c), g1 = *(const f32x4*)(a.gv + c + 4);
;                         f32x4 r0, r1;
; #pragma unroll
;                         for (int j = 0; j < 4; ++j) { r0[j] = x0[j] + sigmoidf_(v[j]) * (e[j] * rs * g0[j]); r1[j] = x1[j] + sigmoidf_(v[4 + j]) * (e[4 + j] * rs * g1[j]); }
;                         *(f32x4*)(a.outf + off) = r0; *(f32x4*)(a.outf + off + 4) = r1;
; __global__ void __launch_bounds__(512, 2) fwd(Params P) {
;     ...
;             const float rsd = __builtin_amdgcn_rsqf(ssq_d[m] * (1.f / DM) + EPS);
;             const u32x2* dr = (const u32x2*)(DN + (size_t)m * DM) + lane;
;             f32x4* orow = (f32x4*)(OUT_P + (size_t)m * DM) + lane; u32x2* o = (u32x2*)(XN + (size_t)m * DM) + lane;
; #pragma unroll
;             for (int j = 0; j < 8; ++j) { const f32x4 xv = __builtin_nontemporal_load(&orow[64 * j]); const u32x2 dw = __builtin_nontemporal_load(&dr[64 * j]); const f32x4 g = g1[64 * j];
;                 f32x4 t; t.x = xv.x + bf_lo(dw.x) * rsd * g.x; t.y = xv.y + bf_hi(dw.x) * rsd * g.y; t.z = xv.z + bf_lo(dw.y) * rsd * g.z; t.w = xv.w + bf_hi(dw.y) * rsd * g.w;
	v_lshlrev_b32_e32 v151, 16, v224
	v_and_b32_e32 v224, 0xffff0000, v224
	v_lshlrev_b32_e32 v159, 16, v225
	v_and_b32_e32 v225, 0xffff0000, v225
	v_lshlrev_b32_e32 v244, 16, v226
	v_and_b32_e32 v226, 0xffff0000, v226
	v_lshlrev_b32_e32 v245, 16, v227
	v_and_b32_e32 v227, 0xffff0000, v227
	v_lshlrev_b32_e32 v240, 16, v236
	v_and_b32_e32 v236, 0xffff0000, v236
	v_lshlrev_b32_e32 v241, 16, v237
	v_and_b32_e32 v237, 0xffff0000, v237
	v_lshlrev_b32_e32 v242, 16, v238
	v_and_b32_e32 v238, 0xffff0000, v238
	v_lshlrev_b32_e32 v243, 16, v239
	v_and_b32_e32 v239, 0xffff0000, v239
	v_mul_f32_e32 v151, v200, v151
	v_mul_f32_e32 v224, v200, v224
	v_mul_f32_e32 v159, v200, v159
	v_mul_f32_e32 v225, v200, v225
	v_mul_f32_e32 v244, v200, v244
	v_mul_f32_e32 v226, v200, v226
	v_mul_f32_e32 v245, v200, v245
	v_mul_f32_e32 v227, v200, v227
	v_mul_f32_e32 v240, v192, v240
	v_mul_f32_e32 v236, v192, v236
	v_mul_f32_e32 v241, v192, v241
	v_mul_f32_e32 v237, v192, v237
	v_mul_f32_e32 v242, v192, v242
	v_mul_f32_e32 v238, v192, v238
	v_mul_f32_e32 v243, v192, v243
	v_mul_f32_e32 v239, v192, v239
	v_fma_f32 v228, v184, v151, v228
	v_fma_f32 v229, v185, v224, v229
	v_fma_f32 v230, v186, v159, v230
	v_fma_f32 v231, v187, v225, v231
	v_fma_f32 v232, v188, v244, v232
	v_fma_f32 v233, v189, v226, v233
	v_fma_f32 v234, v190, v245, v234
	v_fma_f32 v235, v191, v227, v235
	v_mul_f32_e32 v240, v240, v168
	v_mul_f32_e32 v236, v236, v169
	v_mul_f32_e32 v241, v241, v170
	v_mul_f32_e32 v237, v237, v171
	v_mul_f32_e32 v242, v242, v172
	v_mul_f32_e32 v238, v238, v173
	v_mul_f32_e32 v243, v243, v174
	v_mul_f32_e32 v239, v239, v175
	v_fma_f32 v228, v116, v240, v228
	v_fma_f32 v229, v117, v236, v229
	v_fma_f32 v230, v118, v241, v230
	v_fma_f32 v231, v119, v237, v231
	v_fma_f32 v232, v112, v242, v232
	v_fma_f32 v233, v113, v238, v233
	v_fma_f32 v234, v114, v243, v234
	v_fma_f32 v235, v115, v239, v235
	global_store_dwordx4 v150, v[228:231], s[4:5] offset:512
	global_store_dwordx4 v150, v[232:235], s[4:5] offset:528
	s_nop 1
	global_load_dwordx4 v[224:227], v148, s[90:91] offset:256
	global_load_dwordx4 v[228:231], v149, s[4:5] offset:512
	global_load_dwordx4 v[232:235], v149, s[4:5] offset:528
	global_load_dwordx4 v[236:239], v148, s[10:11] offset:256
	v_add_u32_e32 v148, 0x20000, v144
	v_add_u32_e32 v149, 0x40000, v145
	global_load_dwordx4 v[112:115], v148, s[90:91]
	global_load_dwordx4 v[116:119], v149, s[4:5]
	global_load_dwordx4 v[120:123], v149, s[4:5] offset:16
	global_load_dwordx4 v[124:127], v148, s[10:11]
	v_mul_f32_e32 v108, 0xbfb8aa3b, v108
	v_mul_f32_e32 v109, 0xbfb8aa3b, v109
	v_mul_f32_e32 v110, 0xbfb8aa3b, v110
	v_mul_f32_e32 v111, 0xbfb8aa3b, v111
	v_mul_f32_e32 v104, 0xbfb8aa3b, v104
	v_mul_f32_e32 v105, 0xbfb8aa3b, v105
	v_mul_f32_e32 v106, 0xbfb8aa3b, v106
	v_mul_f32_e32 v107, 0xbfb8aa3b, v107
	v_exp_f32_e32 v108, v108
	v_exp_f32_e32 v109, v109
	v_exp_f32_e32 v110, v110
	v_exp_f32_e32 v111, v111
	v_exp_f32_e32 v104, v104
	v_exp_f32_e32 v105, v105
	v_exp_f32_e32 v106, v106
	v_exp_f32_e32 v107, v107
	v_add_f32_e32 v108, 1.0, v108
	v_add_f32_e32 v109, 1.0, v109
	v_add_f32_e32 v110, 1.0, v110
	v_add_f32_e32 v111, 1.0, v111
	v_add_f32_e32 v104, 1.0, v104
	v_add_f32_e32 v105, 1.0, v105
	v_add_f32_e32 v106, 1.0, v106
	v_add_f32_e32 v107, 1.0, v107
	v_rcp_f32_e32 v108, v108
	v_rcp_f32_e32 v109, v109
	v_rcp_f32_e32 v110, v110
	v_rcp_f32_e32 v111, v111
	v_rcp_f32_e32 v104, v104
	v_rcp_f32_e32 v105, v105
	v_rcp_f32_e32 v106, v106
	v_rcp_f32_e32 v107, v107
	s_waitcnt vmcnt(10)
	v_fmamk_f32 v193, v193, 0x3a000000, v158
	v_fmamk_f32 v201, v201, 0x3a000000, v158
	v_rsq_f32_e32 v193, v193
	v_rsq_f32_e32 v201, v201
	v_lshlrev_b32_e32 v151, 16, v208
	v_and_b32_e32 v208, 0xffff0000, v208
	v_lshlrev_b32_e32 v159, 16, v209
	v_and_b32_e32 v209, 0xffff0000, v209
	v_lshlrev_b32_e32 v244, 16, v210
	v_and_b32_e32 v210, 0xffff0000, v210
	v_lshlrev_b32_e32 v245, 16, v211
	v_and_b32_e32 v211, 0xffff0000, v211
	v_lshlrev_b32_e32 v240, 16, v220
	v_and_b32_e32 v220, 0xffff0000, v220
	v_lshlrev_b32_e32 v241, 16, v221
	v_and_b32_e32 v221, 0xffff0000, v221
	v_lshlrev_b32_e32 v242, 16, v222
	v_and_b32_e32 v222, 0xffff0000, v222
	v_lshlrev_b32_e32 v243, 16, v223
	v_and_b32_e32 v223, 0xffff0000, v223
	v_mul_f32_e32 v151, v201, v151
	v_mul_f32_e32 v208, v201, v208
	v_mul_f32_e32 v159, v201, v159
	v_mul_f32_e32 v209, v201, v209
	v_mul_f32_e32 v244, v201, v244
	v_mul_f32_e32 v210, v201, v210
	v_mul_f32_e32 v245, v201, v245
	v_mul_f32_e32 v211, v201, v211
	v_mul_f32_e32 v240, v193, v240
	v_mul_f32_e32 v220, v193, v220
	v_mul_f32_e32 v241, v193, v241
	v_mul_f32_e32 v221, v193, v221
	v_mul_f32_e32 v242, v193, v242
	v_mul_f32_e32 v222, v193, v222
	v_mul_f32_e32 v243, v193, v243
	v_mul_f32_e32 v223, v193, v223
	v_fma_f32 v212, v176, v151, v212
	v_fma_f32 v213, v177, v208, v213
	v_fma_f32 v214, v178, v159, v214
	v_fma_f32 v215, v179, v209, v215
	v_fma_f32 v216, v180, v244, v216
	v_fma_f32 v217, v181, v210, v217
	v_fma_f32 v218, v182, v245, v218
	v_fma_f32 v219, v183, v211, v219
	v_mul_f32_e32 v240, v240, v160
	v_mul_f32_e32 v220, v220, v161
	v_mul_f32_e32 v241, v241, v162
	v_mul_f32_e32 v221, v221, v163
	v_mul_f32_e32 v242, v242, v164
	v_mul_f32_e32 v222, v222, v165
	v_mul_f32_e32 v243, v243, v166
	v_mul_f32_e32 v223, v223, v167
	v_fma_f32 v212, v108, v240, v212
	v_fma_f32 v213, v109, v220, v213
	v_fma_f32 v214, v110, v241, v214
	v_fma_f32 v215, v111, v221, v215
	v_fma_f32 v216, v104, v242, v216
	v_fma_f32 v217, v105, v222, v217
	v_fma_f32 v218, v106, v243, v218
	v_fma_f32 v219, v107, v223, v219
	v_add_u32_e32 v150, 0x20000, v145
	global_store_dwordx4 v150, v[212:215], s[4:5]
	global_store_dwordx4 v150, v[216:219], s[4:5] offset:16
	s_nop 1
	global_load_dwordx4 v[208:211], v148, s[90:91] offset:256
	global_load_dwordx4 v[212:215], v149, s[4:5] offset:512
	global_load_dwordx4 v[216:219], v149, s[4:5] offset:528
	global_load_dwordx4 v[220:223], v148, s[10:11] offset:256
	v_mul_f32_e32 v100, 0xbfb8aa3b, v100
	v_mul_f32_e32 v101, 0xbfb8aa3b, v101
	v_mul_f32_e32 v102, 0xbfb8aa3b, v102
	v_mul_f32_e32 v103, 0xbfb8aa3b, v103
	v_mul_f32_e32 v96, 0xbfb8aa3b, v96
	v_mul_f32_e32 v97, 0xbfb8aa3b, v97
	v_mul_f32_e32 v98, 0xbfb8aa3b, v98
	v_mul_f32_e32 v99, 0xbfb8aa3b, v99
	v_exp_f32_e32 v100, v100
	v_exp_f32_e32 v101, v101
	v_exp_f32_e32 v102, v102
	v_exp_f32_e32 v103, v103
	v_exp_f32_e32 v96, v96
	v_exp_f32_e32 v97, v97
	v_exp_f32_e32 v98, v98
	v_exp_f32_e32 v99, v99
	v_add_f32_e32 v100, 1.0, v100
	v_add_f32_e32 v101, 1.0, v101
	v_add_f32_e32 v102, 1.0, v102
	v_add_f32_e32 v103, 1.0, v103
	v_add_f32_e32 v96, 1.0, v96
	v_add_f32_e32 v97, 1.0, v97
	v_add_f32_e32 v98, 1.0, v98
	v_add_f32_e32 v99, 1.0, v99
	v_rcp_f32_e32 v100, v100
	v_rcp_f32_e32 v101, v101
	v_rcp_f32_e32 v102, v102
	v_rcp_f32_e32 v103, v103
	v_rcp_f32_e32 v96, v96
	v_rcp_f32_e32 v97, v97
	v_rcp_f32_e32 v98, v98
	v_rcp_f32_e32 v99, v99
	s_waitcnt vmcnt(10)
; __device__ __forceinline__ float bf_lo(unsigned w) { return __uint_as_float(w << 16); }
; __device__ __forceinline__ float bf_hi(unsigned w) { return __uint_as_float(w & 0xffff0000u); }
; __device__ __forceinline__ void load8(const bf16_t* src, float* v) { const u32x4 w = *(const u32x4*)src; v[0] = bf_lo(w.x); v[1] = bf_hi(w.x); v[2] = bf_lo(w.y); v[3] = bf_hi(w.y); v[4] = bf_lo(w.z); v[5] = bf_hi(w.z); v[6] = bf_lo(w.w); v[7] = bf_hi(w.w); }
; __device__ __forceinline__ float sigmoidf_(float v) { return __builtin_amdgcn_rcpf(1.f + __builtin_amdgcn_exp2f(-v * LOG2E)); }
;     __device__ __forceinline__ void operator()(const pg8::f32x4 (&acc)[2][2][4][2], const pg8::Unit& u, int wr, int wc, int fr, int fq) const {
;     ...
;                     } else if constexpr (KIND == EK_FIN) {
;                         const int c = pn * 256 + cl; const size_t off = (size_t)row * 2048 + c; float e[8]; load8(a.g0 + off, e);
;                         const f32x4 x0 = *(const f32x4*)(a.outf + off), x1 = *(const f32x4*)(a.outf + off + 4);
;                         const f32x4 g0 = *(const f32x4*)(a.gv + c), g1 = *(const f32x4*)(a.gv + c + 4);
;                         f32x4 r0, r1;
; #pragma unroll
;                         for (int j = 0; j < 4; ++j) { r0[j] = x0[j] + sigmoidf_(v[j]) * (e[j] * rs * g0[j]); r1[j] = x1[j] + sigmoidf_(v[4 + j]) * (e[4 + j] * rs * g1[j]); }
;                         *(f32x4*)(a.outf + off) = r0; *(f32x4*)(a.outf + off + 4) = r1;
; __global__ void __launch_bounds__(512, 2) fwd(Params P) {
;     ...
;             const float rsd = __builtin_amdgcn_rsqf(ssq_d[m] * (1.f / DM) + EPS);
;             const u32x2* dr = (const u32x2*)(DN + (size_t)m * DM) + lane;
;             f32x4* orow = (f32x4*)(OUT_P + (size_t)m * DM) + lane; u32x2* o = (u32x2*)(XN + (size_t)m * DM) + lane;
; #pragma unroll
;             for (int j = 0; j < 8; ++j) { const f32x4 xv = __builtin_nontemporal_load(&orow[64 * j]); const u32x2 dw = __builtin_nontemporal_load(&dr[64 * j]); const f32x4 g = g1[64 * j];
;                 f32x4 t; t.x = xv.x + bf_lo(dw.x) * rsd * g.x; t.y = xv.y + bf_hi(dw.x) * rsd * g.y; t.z = xv.z + bf_lo(dw.y) * rsd * g.z; t.w = xv.w + bf_hi(dw.y) * rsd * g.w;
	v_lshlrev_b32_e32 v151, 16, v224
	v_and_b32_e32 v224, 0xffff0000, v224
	v_lshlrev_b32_e32 v159, 16, v225
	v_and_b32_e32 v225, 0xffff0000, v225
	v_lshlrev_b32_e32 v244, 16, v226
	v_and_b32_e32 v226, 0xffff0000, v226
	v_lshlrev_b32_e32 v245, 16, v227
	v_and_b32_e32 v227, 0xffff0000, v227
	v_lshlrev_b32_e32 v240, 16, v236
	v_and_b32_e32 v236, 0xffff0000, v236
	v_lshlrev_b32_e32 v241, 16, v237
	v_and_b32_e32 v237, 0xffff0000, v237
	v_lshlrev_b32_e32 v242, 16, v238
	v_and_b32_e32 v238, 0xffff0000, v238
	v_lshlrev_b32_e32 v243, 16, v239
	v_and_b32_e32 v239, 0xffff0000, v239
	v_mul_f32_e32 v151, v201, v151
	v_mul_f32_e32 v224, v201, v224
	v_mul_f32_e32 v159, v201, v159
	v_mul_f32_e32 v225, v201, v225
	v_mul_f32_e32 v244, v201, v244
	v_mul_f32_e32 v226, v201, v226
	v_mul_f32_e32 v245, v201, v245
	v_mul_f32_e32 v227, v201, v227
	v_mul_f32_e32 v240, v193, v240
	v_mul_f32_e32 v236, v193, v236
	v_mul_f32_e32 v241, v193, v241
	v_mul_f32_e32 v237, v193, v237
	v_mul_f32_e32 v242, v193, v242
	v_mul_f32_e32 v238, v193, v238
	v_mul_f32_e32 v243, v193, v243
	v_mul_f32_e32 v239, v193, v239
	v_fma_f32 v228, v184, v151, v228
	v_fma_f32 v229, v185, v224, v229
	v_fma_f32 v230, v186, v159, v230
	v_fma_f32 v231, v187, v225, v231
	v_fma_f32 v232, v188, v244, v232
	v_fma_f32 v233, v189, v226, v233
	v_fma_f32 v234, v190, v245, v234
	v_fma_f32 v235, v191, v227, v235
	v_mul_f32_e32 v240, v240, v168
	v_mul_f32_e32 v236, v236, v169
	v_mul_f32_e32 v241, v241, v170
	v_mul_f32_e32 v237, v237, v171
	v_mul_f32_e32 v242, v242, v172
	v_mul_f32_e32 v238, v238, v173
	v_mul_f32_e32 v243, v243, v174
	v_mul_f32_e32 v239, v239, v175
	v_fma_f32 v228, v100, v240, v228
	v_fma_f32 v229, v101, v236, v229
	v_fma_f32 v230, v102, v241, v230
	v_fma_f32 v231, v103, v237, v231
	v_fma_f32 v232, v96, v242, v232
	v_fma_f32 v233, v97, v238, v233
	v_fma_f32 v234, v98, v243, v234
	v_fma_f32 v235, v99, v239, v235
	global_store_dwordx4 v150, v[228:231], s[4:5] offset:512
	global_store_dwordx4 v150, v[232:235], s[4:5] offset:528
	s_nop 1
	v_add_u32_e32 v148, 0x30000, v144
	v_add_u32_e32 v149, 0x60000, v145
	global_load_dwordx4 v[224:227], v148, s[90:91]
	global_load_dwordx4 v[228:231], v149, s[4:5]
	global_load_dwordx4 v[232:235], v149, s[4:5] offset:16
	global_load_dwordx4 v[236:239], v148, s[10:11]
	global_load_dwordx4 v[96:99], v148, s[90:91] offset:256
	global_load_dwordx4 v[100:103], v149, s[4:5] offset:512
	global_load_dwordx4 v[104:107], v149, s[4:5] offset:528
	global_load_dwordx4 v[108:111], v148, s[10:11] offset:256
	v_mul_f32_e32 v92, 0xbfb8aa3b, v92
	v_mul_f32_e32 v93, 0xbfb8aa3b, v93
	v_mul_f32_e32 v94, 0xbfb8aa3b, v94
	v_mul_f32_e32 v95, 0xbfb8aa3b, v95
	v_mul_f32_e32 v88, 0xbfb8aa3b, v88
	v_mul_f32_e32 v89, 0xbfb8aa3b, v89
	v_mul_f32_e32 v90, 0xbfb8aa3b, v90
	v_mul_f32_e32 v91, 0xbfb8aa3b, v91
	v_exp_f32_e32 v92, v92
	v_exp_f32_e32 v93, v93
	v_exp_f32_e32 v94, v94
	v_exp_f32_e32 v95, v95
	v_exp_f32_e32 v88, v88
	v_exp_f32_e32 v89, v89
	v_exp_f32_e32 v90, v90
	v_exp_f32_e32 v91, v91
	v_add_f32_e32 v92, 1.0, v92
	v_add_f32_e32 v93, 1.0, v93
	v_add_f32_e32 v94, 1.0, v94
	v_add_f32_e32 v95, 1.0, v95
	v_add_f32_e32 v88, 1.0, v88
	v_add_f32_e32 v89, 1.0, v89
	v_add_f32_e32 v90, 1.0, v90
	v_add_f32_e32 v91, 1.0, v91
	v_rcp_f32_e32 v92, v92
	v_rcp_f32_e32 v93, v93
	v_rcp_f32_e32 v94, v94
	v_rcp_f32_e32 v95, v95
	v_rcp_f32_e32 v88, v88
	v_rcp_f32_e32 v89, v89
	v_rcp_f32_e32 v90, v90
	v_rcp_f32_e32 v91, v91
	s_waitcnt vmcnt(16)
	v_fmamk_f32 v194, v194, 0x3a000000, v158
	v_fmamk_f32 v202, v202, 0x3a000000, v158
	v_rsq_f32_e32 v194, v194
	v_rsq_f32_e32 v202, v202
	v_lshlrev_b32_e32 v151, 16, v112
	v_and_b32_e32 v112, 0xffff0000, v112
	v_lshlrev_b32_e32 v159, 16, v113
	v_and_b32_e32 v113, 0xffff0000, v113
	v_lshlrev_b32_e32 v244, 16, v114
	v_and_b32_e32 v114, 0xffff0000, v114
	v_lshlrev_b32_e32 v245, 16, v115
	v_and_b32_e32 v115, 0xffff0000, v115
	v_lshlrev_b32_e32 v240, 16, v124
	v_and_b32_e32 v124, 0xffff0000, v124
	v_lshlrev_b32_e32 v241, 16, v125
	v_and_b32_e32 v125, 0xffff0000, v125
	v_lshlrev_b32_e32 v242, 16, v126
	v_and_b32_e32 v126, 0xffff0000, v126
	v_lshlrev_b32_e32 v243, 16, v127
	v_and_b32_e32 v127, 0xffff0000, v127
	v_mul_f32_e32 v151, v202, v151
	v_mul_f32_e32 v112, v202, v112
	v_mul_f32_e32 v159, v202, v159
	v_mul_f32_e32 v113, v202, v113
	v_mul_f32_e32 v244, v202, v244
	v_mul_f32_e32 v114, v202, v114
	v_mul_f32_e32 v245, v202, v245
	v_mul_f32_e32 v115, v202, v115
	v_mul_f32_e32 v240, v194, v240
	v_mul_f32_e32 v124, v194, v124
	v_mul_f32_e32 v241, v194, v241
	v_mul_f32_e32 v125, v194, v125
	v_mul_f32_e32 v242, v194, v242
	v_mul_f32_e32 v126, v194, v126
	v_mul_f32_e32 v243, v194, v243
	v_mul_f32_e32 v127, v194, v127
	v_fma_f32 v116, v176, v151, v116
	v_fma_f32 v117, v177, v112, v117
	v_fma_f32 v118, v178, v159, v118
	v_fma_f32 v119, v179, v113, v119
	v_fma_f32 v120, v180, v244, v120
	v_fma_f32 v121, v181, v114, v121
	v_fma_f32 v122, v182, v245, v122
	v_fma_f32 v123, v183, v115, v123
	v_mul_f32_e32 v240, v240, v160
	v_mul_f32_e32 v124, v124, v161
	v_mul_f32_e32 v241, v241, v162
	v_mul_f32_e32 v125, v125, v163
	v_mul_f32_e32 v242, v242, v164
	v_mul_f32_e32 v126, v126, v165
	v_mul_f32_e32 v243, v243, v166
	v_mul_f32_e32 v127, v127, v167
	v_fma_f32 v116, v92, v240, v116
	v_fma_f32 v117, v93, v124, v117
	v_fma_f32 v118, v94, v241, v118
	v_fma_f32 v119, v95, v125, v119
	v_fma_f32 v120, v88, v242, v120
	v_fma_f32 v121, v89, v126, v121
	v_fma_f32 v122, v90, v243, v122
	v_fma_f32 v123, v91, v127, v123
	v_add_u32_e32 v150, 0x40000, v145
	global_store_dwordx4 v150, v[116:119], s[4:5]
	global_store_dwordx4 v150, v[120:123], s[4:5] offset:16
	s_nop 1
	v_add_u32_e32 v148, 0x80000, v144
	v_add_u32_e32 v149, 0x100000, v145
	global_load_dwordx4 v[112:115], v148, s[90:91]
	global_load_dwordx4 v[116:119], v149, s[4:5]
	global_load_dwordx4 v[120:123], v149, s[4:5] offset:16
	global_load_dwordx4 v[124:127], v148, s[10:11]
	v_mul_f32_e32 v84, 0xbfb8aa3b, v84
	v_mul_f32_e32 v85, 0xbfb8aa3b, v85
	v_mul_f32_e32 v86, 0xbfb8aa3b, v86
	v_mul_f32_e32 v87, 0xbfb8aa3b, v87
	v_mul_f32_e32 v80, 0xbfb8aa3b, v80
	v_mul_f32_e32 v81, 0xbfb8aa3b, v81
	v_mul_f32_e32 v82, 0xbfb8aa3b, v82
	v_mul_f32_e32 v83, 0xbfb8aa3b, v83
	v_exp_f32_e32 v84, v84
	v_exp_f32_e32 v85, v85
	v_exp_f32_e32 v86, v86
	v_exp_f32_e32 v87, v87
	v_exp_f32_e32 v80, v80
	v_exp_f32_e32 v81, v81
	v_exp_f32_e32 v82, v82
	v_exp_f32_e32 v83, v83
	v_add_f32_e32 v84, 1.0, v84
	v_add_f32_e32 v85, 1.0, v85
	v_add_f32_e32 v86, 1.0, v86
	v_add_f32_e32 v87, 1.0, v87
	v_add_f32_e32 v80, 1.0, v80
	v_add_f32_e32 v81, 1.0, v81
	v_add_f32_e32 v82, 1.0, v82
	v_add_f32_e32 v83, 1.0, v83
	v_rcp_f32_e32 v84, v84
	v_rcp_f32_e32 v85, v85
	v_rcp_f32_e32 v86, v86
	v_rcp_f32_e32 v87, v87
	v_rcp_f32_e32 v80, v80
	v_rcp_f32_e32 v81, v81
	v_rcp_f32_e32 v82, v82
	v_rcp_f32_e32 v83, v83
	s_waitcnt vmcnt(16)
; __device__ __forceinline__ float bf_lo(unsigned w) { return __uint_as_float(w << 16); }
; __device__ __forceinline__ float bf_hi(unsigned w) { return __uint_as_float(w & 0xffff0000u); }
; __device__ __forceinline__ void load8(const bf16_t* src, float* v) { const u32x4 w = *(const u32x4*)src; v[0] = bf_lo(w.x); v[1] = bf_hi(w.x); v[2] = bf_lo(w.y); v[3] = bf_hi(w.y); v[4] = bf_lo(w.z); v[5] = bf_hi(w.z); v[6] = bf_lo(w.w); v[7] = bf_hi(w.w); }
; __device__ __forceinline__ float sigmoidf_(float v) { return __builtin_amdgcn_rcpf(1.f + __builtin_amdgcn_exp2f(-v * LOG2E)); }
;     __device__ __forceinline__ void operator()(const pg8::f32x4 (&acc)[2][2][4][2], const pg8::Unit& u, int wr, int wc, int fr, int fq) const {
;     ...
;                     } else if constexpr (KIND == EK_FIN) {
;                         const int c = pn * 256 + cl; const size_t off = (size_t)row * 2048 + c; float e[8]; load8(a.g0 + off, e);
;                         const f32x4 x0 = *(const f32x4*)(a.outf + off), x1 = *(const f32x4*)(a.outf + off + 4);
;                         const f32x4 g0 = *(const f32x4*)(a.gv + c), g1 = *(const f32x4*)(a.gv + c + 4);
;                         f32x4 r0, r1;
; #pragma unroll
;                         for (int j = 0; j < 4; ++j) { r0[j] = x0[j] + sigmoidf_(v[j]) * (e[j] * rs * g0[j]); r1[j] = x1[j] + sigmoidf_(v[4 + j]) * (e[4 + j] * rs * g1[j]); }
;                         *(f32x4*)(a.outf + off) = r0; *(f32x4*)(a.outf + off + 4) = r1;
; __global__ void __launch_bounds__(512, 2) fwd(Params P) {
;     ...
;             const float rsd = __builtin_amdgcn_rsqf(ssq_d[m] * (1.f / DM) + EPS);
;             const u32x2* dr = (const u32x2*)(DN + (size_t)m * DM) + lane;
;             f32x4* orow = (f32x4*)(OUT_P + (size_t)m * DM) + lane; u32x2* o = (u32x2*)(XN + (size_t)m * DM) + lane;
; #pragma unroll
;             for (int j = 0; j < 8; ++j) { const f32x4 xv = __builtin_nontemporal_load(&orow[64 * j]); const u32x2 dw = __builtin_nontemporal_load(&dr[64 * j]); const f32x4 g = g1[64 * j];
;                 f32x4 t; t.x = xv.x + bf_lo(dw.x) * rsd * g.x; t.y = xv.y + bf_hi(dw.x) * rsd * g.y; t.z = xv.z + bf_lo(dw.y) * rsd * g.z; t.w = xv.w + bf_hi(dw.y) * rsd * g.w;
	v_lshlrev_b32_e32 v151, 16, v208
	v_and_b32_e32 v208, 0xffff0000, v208
	v_lshlrev_b32_e32 v159, 16, v209
	v_and_b32_e32 v209, 0xffff0000, v209
	v_lshlrev_b32_e32 v244, 16, v210
	v_and_b32_e32 v210, 0xffff0000, v210
	v_lshlrev_b32_e32 v245, 16, v211
	v_and_b32_e32 v211, 0xffff0000, v211
	v_lshlrev_b32_e32 v240, 16, v220
	v_and_b32_e32 v220, 0xffff0000, v220
	v_lshlrev_b32_e32 v241, 16, v221
	v_and_b32_e32 v221, 0xffff0000, v221
	v_lshlrev_b32_e32 v242, 16, v222
	v_and_b32_e32 v222, 0xffff0000, v222
	v_lshlrev_b32_e32 v243, 16, v223
	v_and_b32_e32 v223, 0xffff0000, v223
	v_mul_f32_e32 v151, v202, v151
	v_mul_f32_e32 v208, v202, v208
	v_mul_f32_e32 v159, v202, v159
	v_mul_f32_e32 v209, v202, v209
	v_mul_f32_e32 v244, v202, v244
	v_mul_f32_e32 v210, v202, v210
	v_mul_f32_e32 v245, v202, v245
	v_mul_f32_e32 v211, v202, v211
	v_mul_f32_e32 v240, v194, v240
	v_mul_f32_e32 v220, v194, v220
	v_mul_f32_e32 v241, v194, v241
	v_mul_f32_e32 v221, v194, v221
	v_mul_f32_e32 v242, v194, v242
	v_mul_f32_e32 v222, v194, v222
	v_mul_f32_e32 v243, v194, v243
	v_mul_f32_e32 v223, v194, v223
	v_fma_f32 v212, v184, v151, v212
	v_fma_f32 v213, v185, v208, v213
	v_fma_f32 v214, v186, v159, v214
	v_fma_f32 v215, v187, v209, v215
	v_fma_f32 v216, v188, v244, v216
	v_fma_f32 v217, v189, v210, v217
	v_fma_f32 v218, v190, v245, v218
	v_fma_f32 v219, v191, v211, v219
	v_mul_f32_e32 v240, v240, v168
	v_mul_f32_e32 v220, v220, v169
	v_mul_f32_e32 v241, v241, v170
	v_mul_f32_e32 v221, v221, v171
	v_mul_f32_e32 v242, v242, v172
	v_mul_f32_e32 v222, v222, v173
	v_mul_f32_e32 v243, v243, v174
	v_mul_f32_e32 v223, v223, v175
	v_fma_f32 v212, v84, v240, v212
	v_fma_f32 v213, v85, v220, v213
	v_fma_f32 v214, v86, v241, v214
	v_fma_f32 v215, v87, v221, v215
	v_fma_f32 v216, v80, v242, v216
	v_fma_f32 v217, v81, v222, v217
	v_fma_f32 v218, v82, v243, v218
	v_fma_f32 v219, v83, v223, v219
	global_store_dwordx4 v150, v[212:215], s[4:5] offset:512
	global_store_dwordx4 v150, v[216:219], s[4:5] offset:528
	s_nop 1
	global_load_dwordx4 v[208:211], v148, s[90:91] offset:256
	global_load_dwordx4 v[212:215], v149, s[4:5] offset:512
	global_load_dwordx4 v[216:219], v149, s[4:5] offset:528
	global_load_dwordx4 v[220:223], v148, s[10:11] offset:256
	v_mul_f32_e32 v76, 0xbfb8aa3b, v76
	v_mul_f32_e32 v77, 0xbfb8aa3b, v77
	v_mul_f32_e32 v78, 0xbfb8aa3b, v78
	v_mul_f32_e32 v79, 0xbfb8aa3b, v79
	v_mul_f32_e32 v72, 0xbfb8aa3b, v72
	v_mul_f32_e32 v73, 0xbfb8aa3b, v73
	v_mul_f32_e32 v74, 0xbfb8aa3b, v74
	v_mul_f32_e32 v75, 0xbfb8aa3b, v75
	v_exp_f32_e32 v76, v76
	v_exp_f32_e32 v77, v77
	v_exp_f32_e32 v78, v78
	v_exp_f32_e32 v79, v79
	v_exp_f32_e32 v72, v72
	v_exp_f32_e32 v73, v73
	v_exp_f32_e32 v74, v74
	v_exp_f32_e32 v75, v75
	v_add_f32_e32 v76, 1.0, v76
	v_add_f32_e32 v77, 1.0, v77
	v_add_f32_e32 v78, 1.0, v78
	v_add_f32_e32 v79, 1.0, v79
	v_add_f32_e32 v72, 1.0, v72
	v_add_f32_e32 v73, 1.0, v73
	v_add_f32_e32 v74, 1.0, v74
	v_add_f32_e32 v75, 1.0, v75
	v_rcp_f32_e32 v76, v76
	v_rcp_f32_e32 v77, v77
	v_rcp_f32_e32 v78, v78
	v_rcp_f32_e32 v79, v79
	v_rcp_f32_e32 v72, v72
	v_rcp_f32_e32 v73, v73
	v_rcp_f32_e32 v74, v74
	v_rcp_f32_e32 v75, v75
	s_waitcnt vmcnt(16)
	v_fmamk_f32 v195, v195, 0x3a000000, v158
	v_fmamk_f32 v203, v203, 0x3a000000, v158
	v_rsq_f32_e32 v195, v195
	v_rsq_f32_e32 v203, v203
	v_lshlrev_b32_e32 v151, 16, v224
	v_and_b32_e32 v224, 0xffff0000, v224
	v_lshlrev_b32_e32 v159, 16, v225
	v_and_b32_e32 v225, 0xffff0000, v225
	v_lshlrev_b32_e32 v244, 16, v226
	v_and_b32_e32 v226, 0xffff0000, v226
	v_lshlrev_b32_e32 v245, 16, v227
	v_and_b32_e32 v227, 0xffff0000, v227
	v_lshlrev_b32_e32 v240, 16, v236
	v_and_b32_e32 v236, 0xffff0000, v236
	v_lshlrev_b32_e32 v241, 16, v237
	v_and_b32_e32 v237, 0xffff0000, v237
	v_lshlrev_b32_e32 v242, 16, v238
	v_and_b32_e32 v238, 0xffff0000, v238
	v_lshlrev_b32_e32 v243, 16, v239
	v_and_b32_e32 v239, 0xffff0000, v239
	v_mul_f32_e32 v151, v203, v151
	v_mul_f32_e32 v224, v203, v224
	v_mul_f32_e32 v159, v203, v159
	v_mul_f32_e32 v225, v203, v225
	v_mul_f32_e32 v244, v203, v244
	v_mul_f32_e32 v226, v203, v226
	v_mul_f32_e32 v245, v203, v245
	v_mul_f32_e32 v227, v203, v227
	v_mul_f32_e32 v240, v195, v240
	v_mul_f32_e32 v236, v195, v236
	v_mul_f32_e32 v241, v195, v241
	v_mul_f32_e32 v237, v195, v237
	v_mul_f32_e32 v242, v195, v242
	v_mul_f32_e32 v238, v195, v238
	v_mul_f32_e32 v243, v195, v243
	v_mul_f32_e32 v239, v195, v239
	v_fma_f32 v228, v176, v151, v228
	v_fma_f32 v229, v177, v224, v229
	v_fma_f32 v230, v178, v159, v230
	v_fma_f32 v231, v179, v225, v231
	v_fma_f32 v232, v180, v244, v232
	v_fma_f32 v233, v181, v226, v233
	v_fma_f32 v234, v182, v245, v234
	v_fma_f32 v235, v183, v227, v235
	v_mul_f32_e32 v240, v240, v160
	v_mul_f32_e32 v236, v236, v161
	v_mul_f32_e32 v241, v241, v162
	v_mul_f32_e32 v237, v237, v163
	v_mul_f32_e32 v242, v242, v164
	v_mul_f32_e32 v238, v238, v165
	v_mul_f32_e32 v243, v243, v166
	v_mul_f32_e32 v239, v239, v167
	v_fma_f32 v228, v76, v240, v228
	v_fma_f32 v229, v77, v236, v229
	v_fma_f32 v230, v78, v241, v230
	v_fma_f32 v231, v79, v237, v231
	v_fma_f32 v232, v72, v242, v232
	v_fma_f32 v233, v73, v238, v233
	v_fma_f32 v234, v74, v243, v234
	v_fma_f32 v235, v75, v239, v235
	v_add_u32_e32 v150, 0x60000, v145
	global_store_dwordx4 v150, v[228:231], s[4:5]
	global_store_dwordx4 v150, v[232:235], s[4:5] offset:16
	s_nop 1
	v_add_u32_e32 v148, 0x90000, v144
	v_add_u32_e32 v149, 0x120000, v145
	global_load_dwordx4 v[80:83], v148, s[90:91]
	global_load_dwordx4 v[84:87], v149, s[4:5]
	global_load_dwordx4 v[88:91], v149, s[4:5] offset:16
	global_load_dwordx4 v[92:95], v148, s[10:11]
	v_mul_f32_e32 v68, 0xbfb8aa3b, v68
	v_mul_f32_e32 v69, 0xbfb8aa3b, v69
	v_mul_f32_e32 v70, 0xbfb8aa3b, v70
	v_mul_f32_e32 v71, 0xbfb8aa3b, v71
	v_mul_f32_e32 v64, 0xbfb8aa3b, v64
	v_mul_f32_e32 v65, 0xbfb8aa3b, v65
	v_mul_f32_e32 v66, 0xbfb8aa3b, v66
	v_mul_f32_e32 v67, 0xbfb8aa3b, v67
	v_exp_f32_e32 v68, v68
	v_exp_f32_e32 v69, v69
	v_exp_f32_e32 v70, v70
	v_exp_f32_e32 v71, v71
	v_exp_f32_e32 v64, v64
	v_exp_f32_e32 v65, v65
	v_exp_f32_e32 v66, v66
	v_exp_f32_e32 v67, v67
	v_add_f32_e32 v68, 1.0, v68
	v_add_f32_e32 v69, 1.0, v69
	v_add_f32_e32 v70, 1.0, v70
	v_add_f32_e32 v71, 1.0, v71
	v_add_f32_e32 v64, 1.0, v64
	v_add_f32_e32 v65, 1.0, v65
	v_add_f32_e32 v66, 1.0, v66
	v_add_f32_e32 v67, 1.0, v67
	v_rcp_f32_e32 v68, v68
	v_rcp_f32_e32 v69, v69
	v_rcp_f32_e32 v70, v70
	v_rcp_f32_e32 v71, v71
	v_rcp_f32_e32 v64, v64
	v_rcp_f32_e32 v65, v65
	v_rcp_f32_e32 v66, v66
	v_rcp_f32_e32 v67, v67
	s_waitcnt vmcnt(18)
; __device__ __forceinline__ float bf_lo(unsigned w) { return __uint_as_float(w << 16); }
; __device__ __forceinline__ float bf_hi(unsigned w) { return __uint_as_float(w & 0xffff0000u); }
; __device__ __forceinline__ void load8(const bf16_t* src, float* v) { const u32x4 w = *(const u32x4*)src; v[0] = bf_lo(w.x); v[1] = bf_hi(w.x); v[2] = bf_lo(w.y); v[3] = bf_hi(w.y); v[4] = bf_lo(w.z); v[5] = bf_hi(w.z); v[6] = bf_lo(w.w); v[7] = bf_hi(w.w); }
; __device__ __forceinline__ float sigmoidf_(float v) { return __builtin_amdgcn_rcpf(1.f + __builtin_amdgcn_exp2f(-v * LOG2E)); }
;     __device__ __forceinline__ void operator()(const pg8::f32x4 (&acc)[2][2][4][2], const pg8::Unit& u, int wr, int wc, int fr, int fq) const {
;     ...
;                     } else if constexpr (KIND == EK_FIN) {
;                         const int c = pn * 256 + cl; const size_t off = (size_t)row * 2048 + c; float e[8]; load8(a.g0 + off, e);
;                         const f32x4 x0 = *(const f32x4*)(a.outf + off), x1 = *(const f32x4*)(a.outf + off + 4);
;                         const f32x4 g0 = *(const f32x4*)(a.gv + c), g1 = *(const f32x4*)(a.gv + c + 4);
;                         f32x4 r0, r1;
; #pragma unroll
;                         for (int j = 0; j < 4; ++j) { r0[j] = x0[j] + sigmoidf_(v[j]) * (e[j] * rs * g0[j]); r1[j] = x1[j] + sigmoidf_(v[4 + j]) * (e[4 + j] * rs * g1[j]); }
;                         *(f32x4*)(a.outf + off) = r0; *(f32x4*)(a.outf + off + 4) = r1;
; __global__ void __launch_bounds__(512, 2) fwd(Params P) {
;     ...
;             const float rsd = __builtin_amdgcn_rsqf(ssq_d[m] * (1.f / DM) + EPS);
;             const u32x2* dr = (const u32x2*)(DN + (size_t)m * DM) + lane;
;             f32x4* orow = (f32x4*)(OUT_P + (size_t)m * DM) + lane; u32x2* o = (u32x2*)(XN + (size_t)m * DM) + lane;
; #pragma unroll
;             for (int j = 0; j < 8; ++j) { const f32x4 xv = __builtin_nontemporal_load(&orow[64 * j]); const u32x2 dw = __builtin_nontemporal_load(&dr[64 * j]); const f32x4 g = g1[64 * j];
;                 f32x4 t; t.x = xv.x + bf_lo(dw.x) * rsd * g.x; t.y = xv.y + bf_hi(dw.x) * rsd * g.y; t.z = xv.z + bf_lo(dw.y) * rsd * g.z; t.w = xv.w + bf_hi(dw.y) * rsd * g.w;
	v_lshlrev_b32_e32 v151, 16, v96
	v_and_b32_e32 v96, 0xffff0000, v96
	v_lshlrev_b32_e32 v159, 16, v97
	v_and_b32_e32 v97, 0xffff0000, v97
	v_lshlrev_b32_e32 v244, 16, v98
	v_and_b32_e32 v98, 0xffff0000, v98
	v_lshlrev_b32_e32 v245, 16, v99
	v_and_b32_e32 v99, 0xffff0000, v99
	v_lshlrev_b32_e32 v240, 16, v108
	v_and_b32_e32 v108, 0xffff0000, v108
	v_lshlrev_b32_e32 v241, 16, v109
	v_and_b32_e32 v109, 0xffff0000, v109
	v_lshlrev_b32_e32 v242, 16, v110
	v_and_b32_e32 v110, 0xffff0000, v110
	v_lshlrev_b32_e32 v243, 16, v111
	v_and_b32_e32 v111, 0xffff0000, v111
	v_mul_f32_e32 v151, v203, v151
	v_mul_f32_e32 v96, v203, v96
	v_mul_f32_e32 v159, v203, v159
	v_mul_f32_e32 v97, v203, v97
	v_mul_f32_e32 v244, v203, v244
	v_mul_f32_e32 v98, v203, v98
	v_mul_f32_e32 v245, v203, v245
	v_mul_f32_e32 v99, v203, v99
	v_mul_f32_e32 v240, v195, v240
	v_mul_f32_e32 v108, v195, v108
	v_mul_f32_e32 v241, v195, v241
	v_mul_f32_e32 v109, v195, v109
	v_mul_f32_e32 v242, v195, v242
	v_mul_f32_e32 v110, v195, v110
	v_mul_f32_e32 v243, v195, v243
	v_mul_f32_e32 v111, v195, v111
	v_fma_f32 v100, v184, v151, v100
	v_fma_f32 v101, v185, v96, v101
	v_fma_f32 v102, v186, v159, v102
	v_fma_f32 v103, v187, v97, v103
	v_fma_f32 v104, v188, v244, v104
	v_fma_f32 v105, v189, v98, v105
	v_fma_f32 v106, v190, v245, v106
	v_fma_f32 v107, v191, v99, v107
	v_mul_f32_e32 v240, v240, v168
	v_mul_f32_e32 v108, v108, v169
	v_mul_f32_e32 v241, v241, v170
	v_mul_f32_e32 v109, v109, v171
	v_mul_f32_e32 v242, v242, v172
	v_mul_f32_e32 v110, v110, v173
	v_mul_f32_e32 v243, v243, v174
	v_mul_f32_e32 v111, v111, v175
	v_fma_f32 v100, v68, v240, v100
	v_fma_f32 v101, v69, v108, v101
	v_fma_f32 v102, v70, v241, v102
	v_fma_f32 v103, v71, v109, v103
	v_fma_f32 v104, v64, v242, v104
	v_fma_f32 v105, v65, v110, v105
	v_fma_f32 v106, v66, v243, v106
	v_fma_f32 v107, v67, v111, v107
	global_store_dwordx4 v150, v[100:103], s[4:5] offset:512
	global_store_dwordx4 v150, v[104:107], s[4:5] offset:528
	s_nop 1
	global_load_dwordx4 v[224:227], v148, s[90:91] offset:256
	global_load_dwordx4 v[228:231], v149, s[4:5] offset:512
	global_load_dwordx4 v[232:235], v149, s[4:5] offset:528
	global_load_dwordx4 v[236:239], v148, s[10:11] offset:256
	v_mul_f32_e32 v60, 0xbfb8aa3b, v60
	v_mul_f32_e32 v61, 0xbfb8aa3b, v61
	v_mul_f32_e32 v62, 0xbfb8aa3b, v62
	v_mul_f32_e32 v63, 0xbfb8aa3b, v63
	v_mul_f32_e32 v56, 0xbfb8aa3b, v56
	v_mul_f32_e32 v57, 0xbfb8aa3b, v57
	v_mul_f32_e32 v58, 0xbfb8aa3b, v58
	v_mul_f32_e32 v59, 0xbfb8aa3b, v59
	v_exp_f32_e32 v60, v60
	v_exp_f32_e32 v61, v61
	v_exp_f32_e32 v62, v62
	v_exp_f32_e32 v63, v63
	v_exp_f32_e32 v56, v56
	v_exp_f32_e32 v57, v57
	v_exp_f32_e32 v58, v58
	v_exp_f32_e32 v59, v59
	v_add_f32_e32 v60, 1.0, v60
	v_add_f32_e32 v61, 1.0, v61
	v_add_f32_e32 v62, 1.0, v62
	v_add_f32_e32 v63, 1.0, v63
	v_add_f32_e32 v56, 1.0, v56
	v_add_f32_e32 v57, 1.0, v57
	v_add_f32_e32 v58, 1.0, v58
	v_add_f32_e32 v59, 1.0, v59
	v_rcp_f32_e32 v60, v60
	v_rcp_f32_e32 v61, v61
	v_rcp_f32_e32 v62, v62
	v_rcp_f32_e32 v63, v63
	v_rcp_f32_e32 v56, v56
	v_rcp_f32_e32 v57, v57
	v_rcp_f32_e32 v58, v58
	v_rcp_f32_e32 v59, v59
	s_waitcnt vmcnt(18)
	v_fmamk_f32 v196, v196, 0x3a000000, v158
	v_fmamk_f32 v204, v204, 0x3a000000, v158
	v_rsq_f32_e32 v196, v196
	v_rsq_f32_e32 v204, v204
	v_lshlrev_b32_e32 v151, 16, v112
	v_and_b32_e32 v112, 0xffff0000, v112
	v_lshlrev_b32_e32 v159, 16, v113
	v_and_b32_e32 v113, 0xffff0000, v113
	v_lshlrev_b32_e32 v244, 16, v114
	v_and_b32_e32 v114, 0xffff0000, v114
	v_lshlrev_b32_e32 v245, 16, v115
	v_and_b32_e32 v115, 0xffff0000, v115
	v_lshlrev_b32_e32 v240, 16, v124
	v_and_b32_e32 v124, 0xffff0000, v124
	v_lshlrev_b32_e32 v241, 16, v125
	v_and_b32_e32 v125, 0xffff0000, v125
	v_lshlrev_b32_e32 v242, 16, v126
	v_and_b32_e32 v126, 0xffff0000, v126
	v_lshlrev_b32_e32 v243, 16, v127
	v_and_b32_e32 v127, 0xffff0000, v127
	v_mul_f32_e32 v151, v204, v151
	v_mul_f32_e32 v112, v204, v112
	v_mul_f32_e32 v159, v204, v159
	v_mul_f32_e32 v113, v204, v113
	v_mul_f32_e32 v244, v204, v244
	v_mul_f32_e32 v114, v204, v114
	v_mul_f32_e32 v245, v204, v245
	v_mul_f32_e32 v115, v204, v115
	v_mul_f32_e32 v240, v196, v240
	v_mul_f32_e32 v124, v196, v124
	v_mul_f32_e32 v241, v196, v241
	v_mul_f32_e32 v125, v196, v125
	v_mul_f32_e32 v242, v196, v242
	v_mul_f32_e32 v126, v196, v126
	v_mul_f32_e32 v243, v196, v243
	v_mul_f32_e32 v127, v196, v127
	v_fma_f32 v116, v176, v151, v116
	v_fma_f32 v117, v177, v112, v117
	v_fma_f32 v118, v178, v159, v118
	v_fma_f32 v119, v179, v113, v119
	v_fma_f32 v120, v180, v244, v120
	v_fma_f32 v121, v181, v114, v121
	v_fma_f32 v122, v182, v245, v122
	v_fma_f32 v123, v183, v115, v123
	v_mul_f32_e32 v240, v240, v160
	v_mul_f32_e32 v124, v124, v161
	v_mul_f32_e32 v241, v241, v162
	v_mul_f32_e32 v125, v125, v163
	v_mul_f32_e32 v242, v242, v164
	v_mul_f32_e32 v126, v126, v165
	v_mul_f32_e32 v243, v243, v166
	v_mul_f32_e32 v127, v127, v167
	v_fma_f32 v116, v60, v240, v116
	v_fma_f32 v117, v61, v124, v117
	v_fma_f32 v118, v62, v241, v118
	v_fma_f32 v119, v63, v125, v119
	v_fma_f32 v120, v56, v242, v120
	v_fma_f32 v121, v57, v126, v121
	v_fma_f32 v122, v58, v243, v122
	v_fma_f32 v123, v59, v127, v123
	v_add_u32_e32 v150, 0x100000, v145
	global_store_dwordx4 v150, v[116:119], s[4:5]
	global_store_dwordx4 v150, v[120:123], s[4:5] offset:16
	s_nop 1
	v_add_u32_e32 v148, 0xa0000, v144
	v_add_u32_e32 v149, 0x140000, v145
	global_load_dwordx4 v[96:99], v148, s[90:91]
	global_load_dwordx4 v[100:103], v149, s[4:5]
	global_load_dwordx4 v[104:107], v149, s[4:5] offset:16
	global_load_dwordx4 v[108:111], v148, s[10:11]
	v_mul_f32_e32 v52, 0xbfb8aa3b, v52
	v_mul_f32_e32 v53, 0xbfb8aa3b, v53
	v_mul_f32_e32 v54, 0xbfb8aa3b, v54
	v_mul_f32_e32 v55, 0xbfb8aa3b, v55
	v_mul_f32_e32 v48, 0xbfb8aa3b, v48
	v_mul_f32_e32 v49, 0xbfb8aa3b, v49
	v_mul_f32_e32 v50, 0xbfb8aa3b, v50
	v_mul_f32_e32 v51, 0xbfb8aa3b, v51
	v_exp_f32_e32 v52, v52
	v_exp_f32_e32 v53, v53
	v_exp_f32_e32 v54, v54
	v_exp_f32_e32 v55, v55
	v_exp_f32_e32 v48, v48
	v_exp_f32_e32 v49, v49
	v_exp_f32_e32 v50, v50
	v_exp_f32_e32 v51, v51
	v_add_f32_e32 v52, 1.0, v52
	v_add_f32_e32 v53, 1.0, v53
	v_add_f32_e32 v54, 1.0, v54
	v_add_f32_e32 v55, 1.0, v55
	v_add_f32_e32 v48, 1.0, v48
	v_add_f32_e32 v49, 1.0, v49
	v_add_f32_e32 v50, 1.0, v50
	v_add_f32_e32 v51, 1.0, v51
	v_rcp_f32_e32 v52, v52
	v_rcp_f32_e32 v53, v53
	v_rcp_f32_e32 v54, v54
	v_rcp_f32_e32 v55, v55
	v_rcp_f32_e32 v48, v48
	v_rcp_f32_e32 v49, v49
	v_rcp_f32_e32 v50, v50
	v_rcp_f32_e32 v51, v51
	s_waitcnt vmcnt(18)
; __device__ __forceinline__ float bf_lo(unsigned w) { return __uint_as_float(w << 16); }
; __device__ __forceinline__ float bf_hi(unsigned w) { return __uint_as_float(w & 0xffff0000u); }
; __device__ __forceinline__ void load8(const bf16_t* src, float* v) { const u32x4 w = *(const u32x4*)src; v[0] = bf_lo(w.x); v[1] = bf_hi(w.x); v[2] = bf_lo(w.y); v[3] = bf_hi(w.y); v[4] = bf_lo(w.z); v[5] = bf_hi(w.z); v[6] = bf_lo(w.w); v[7] = bf_hi(w.w); }
; __device__ __forceinline__ float sigmoidf_(float v) { return __builtin_amdgcn_rcpf(1.f + __builtin_amdgcn_exp2f(-v * LOG2E)); }
;     __device__ __forceinline__ void operator()(const pg8::f32x4 (&acc)[2][2][4][2], const pg8::Unit& u, int wr, int wc, int fr, int fq) const {
;     ...
;                     } else if constexpr (KIND == EK_FIN) {
;                         const int c = pn * 256 + cl; const size_t off = (size_t)row * 2048 + c; float e[8]; load8(a.g0 + off, e);
;                         const f32x4 x0 = *(const f32x4*)(a.outf + off), x1 = *(const f32x4*)(a.outf + off + 4);
;                         const f32x4 g0 = *(const f32x4*)(a.gv + c), g1 = *(const f32x4*)(a.gv + c + 4);
;                         f32x4 r0, r1;
; #pragma unroll
;                         for (int j = 0; j < 4; ++j) { r0[j] = x0[j] + sigmoidf_(v[j]) * (e[j] * rs * g0[j]); r1[j] = x1[j] + sigmoidf_(v[4 + j]) * (e[4 + j] * rs * g1[j]); }
;                         *(f32x4*)(a.outf + off) = r0; *(f32x4*)(a.outf + off + 4) = r1;
; __global__ void __launch_bounds__(512, 2) fwd(Params P) {
;     ...
;             const float rsd = __builtin_amdgcn_rsqf(ssq_d[m] * (1.f / DM) + EPS);
;             const u32x2* dr = (const u32x2*)(DN + (size_t)m * DM) + lane;
;             f32x4* orow = (f32x4*)(OUT_P + (size_t)m * DM) + lane; u32x2* o = (u32x2*)(XN + (size_t)m * DM) + lane;
; #pragma unroll
;             for (int j = 0; j < 8; ++j) { const f32x4 xv = __builtin_nontemporal_load(&orow[64 * j]); const u32x2 dw = __builtin_nontemporal_load(&dr[64 * j]); const f32x4 g = g1[64 * j];
;                 f32x4 t; t.x = xv.x + bf_lo(dw.x) * rsd * g.x; t.y = xv.y + bf_hi(dw.x) * rsd * g.y; t.z = xv.z + bf_lo(dw.y) * rsd * g.z; t.w = xv.w + bf_hi(dw.y) * rsd * g.w;
	v_lshlrev_b32_e32 v151, 16, v208
	v_and_b32_e32 v208, 0xffff0000, v208
	v_lshlrev_b32_e32 v159, 16, v209
	v_and_b32_e32 v209, 0xffff0000, v209
	v_lshlrev_b32_e32 v244, 16, v210
	v_and_b32_e32 v210, 0xffff0000, v210
	v_lshlrev_b32_e32 v245, 16, v211
	v_and_b32_e32 v211, 0xffff0000, v211
	v_lshlrev_b32_e32 v240, 16, v220
	v_and_b32_e32 v220, 0xffff0000, v220
	v_lshlrev_b32_e32 v241, 16, v221
	v_and_b32_e32 v221, 0xffff0000, v221
	v_lshlrev_b32_e32 v242, 16, v222
	v_and_b32_e32 v222, 0xffff0000, v222
	v_lshlrev_b32_e32 v243, 16, v223
	v_and_b32_e32 v223, 0xffff0000, v223
	v_mul_f32_e32 v151, v204, v151
	v_mul_f32_e32 v208, v204, v208
	v_mul_f32_e32 v159, v204, v159
	v_mul_f32_e32 v209, v204, v209
	v_mul_f32_e32 v244, v204, v244
	v_mul_f32_e32 v210, v204, v210
	v_mul_f32_e32 v245, v204, v245
	v_mul_f32_e32 v211, v204, v211
	v_mul_f32_e32 v240, v196, v240
	v_mul_f32_e32 v220, v196, v220
	v_mul_f32_e32 v241, v196, v241
	v_mul_f32_e32 v221, v196, v221
	v_mul_f32_e32 v242, v196, v242
	v_mul_f32_e32 v222, v196, v222
	v_mul_f32_e32 v243, v196, v243
	v_mul_f32_e32 v223, v196, v223
	v_fma_f32 v212, v184, v151, v212
	v_fma_f32 v213, v185, v208, v213
	v_fma_f32 v214, v186, v159, v214
	v_fma_f32 v215, v187, v209, v215
	v_fma_f32 v216, v188, v244, v216
	v_fma_f32 v217, v189, v210, v217
	v_fma_f32 v218, v190, v245, v218
	v_fma_f32 v219, v191, v211, v219
	v_mul_f32_e32 v240, v240, v168
	v_mul_f32_e32 v220, v220, v169
	v_mul_f32_e32 v241, v241, v170
	v_mul_f32_e32 v221, v221, v171
	v_mul_f32_e32 v242, v242, v172
	v_mul_f32_e32 v222, v222, v173
	v_mul_f32_e32 v243, v243, v174
	v_mul_f32_e32 v223, v223, v175
	v_fma_f32 v212, v52, v240, v212
	v_fma_f32 v213, v53, v220, v213
	v_fma_f32 v214, v54, v241, v214
	v_fma_f32 v215, v55, v221, v215
	v_fma_f32 v216, v48, v242, v216
	v_fma_f32 v217, v49, v222, v217
	v_fma_f32 v218, v50, v243, v218
	v_fma_f32 v219, v51, v223, v219
	global_store_dwordx4 v150, v[212:215], s[4:5] offset:512
	global_store_dwordx4 v150, v[216:219], s[4:5] offset:528
	s_nop 1
	global_load_dwordx4 v[64:67], v148, s[90:91] offset:256
	global_load_dwordx4 v[68:71], v149, s[4:5] offset:512
	global_load_dwordx4 v[72:75], v149, s[4:5] offset:528
	global_load_dwordx4 v[76:79], v148, s[10:11] offset:256
	v_mul_f32_e32 v44, 0xbfb8aa3b, v44
	v_mul_f32_e32 v45, 0xbfb8aa3b, v45
	v_mul_f32_e32 v46, 0xbfb8aa3b, v46
	v_mul_f32_e32 v47, 0xbfb8aa3b, v47
	v_mul_f32_e32 v40, 0xbfb8aa3b, v40
	v_mul_f32_e32 v41, 0xbfb8aa3b, v41
	v_mul_f32_e32 v42, 0xbfb8aa3b, v42
	v_mul_f32_e32 v43, 0xbfb8aa3b, v43
	v_exp_f32_e32 v44, v44
	v_exp_f32_e32 v45, v45
	v_exp_f32_e32 v46, v46
	v_exp_f32_e32 v47, v47
	v_exp_f32_e32 v40, v40
	v_exp_f32_e32 v41, v41
	v_exp_f32_e32 v42, v42
	v_exp_f32_e32 v43, v43
	v_add_f32_e32 v44, 1.0, v44
	v_add_f32_e32 v45, 1.0, v45
	v_add_f32_e32 v46, 1.0, v46
	v_add_f32_e32 v47, 1.0, v47
	v_add_f32_e32 v40, 1.0, v40
	v_add_f32_e32 v41, 1.0, v41
	v_add_f32_e32 v42, 1.0, v42
	v_add_f32_e32 v43, 1.0, v43
	v_rcp_f32_e32 v44, v44
	v_rcp_f32_e32 v45, v45
	v_rcp_f32_e32 v46, v46
	v_rcp_f32_e32 v47, v47
	v_rcp_f32_e32 v40, v40
	v_rcp_f32_e32 v41, v41
	v_rcp_f32_e32 v42, v42
	v_rcp_f32_e32 v43, v43
	s_waitcnt vmcnt(18)
	v_fmamk_f32 v197, v197, 0x3a000000, v158
	v_fmamk_f32 v205, v205, 0x3a000000, v158
	v_rsq_f32_e32 v197, v197
	v_rsq_f32_e32 v205, v205
	v_lshlrev_b32_e32 v151, 16, v80
	v_and_b32_e32 v80, 0xffff0000, v80
	v_lshlrev_b32_e32 v159, 16, v81
	v_and_b32_e32 v81, 0xffff0000, v81
	v_lshlrev_b32_e32 v244, 16, v82
	v_and_b32_e32 v82, 0xffff0000, v82
	v_lshlrev_b32_e32 v245, 16, v83
	v_and_b32_e32 v83, 0xffff0000, v83
	v_lshlrev_b32_e32 v240, 16, v92
	v_and_b32_e32 v92, 0xffff0000, v92
	v_lshlrev_b32_e32 v241, 16, v93
	v_and_b32_e32 v93, 0xffff0000, v93
	v_lshlrev_b32_e32 v242, 16, v94
	v_and_b32_e32 v94, 0xffff0000, v94
	v_lshlrev_b32_e32 v243, 16, v95
	v_and_b32_e32 v95, 0xffff0000, v95
	v_mul_f32_e32 v151, v205, v151
	v_mul_f32_e32 v80, v205, v80
	v_mul_f32_e32 v159, v205, v159
	v_mul_f32_e32 v81, v205, v81
	v_mul_f32_e32 v244, v205, v244
	v_mul_f32_e32 v82, v205, v82
	v_mul_f32_e32 v245, v205, v245
	v_mul_f32_e32 v83, v205, v83
	v_mul_f32_e32 v240, v197, v240
	v_mul_f32_e32 v92, v197, v92
	v_mul_f32_e32 v241, v197, v241
	v_mul_f32_e32 v93, v197, v93
	v_mul_f32_e32 v242, v197, v242
	v_mul_f32_e32 v94, v197, v94
	v_mul_f32_e32 v243, v197, v243
	v_mul_f32_e32 v95, v197, v95
	v_fma_f32 v84, v176, v151, v84
	v_fma_f32 v85, v177, v80, v85
	v_fma_f32 v86, v178, v159, v86
	v_fma_f32 v87, v179, v81, v87
	v_fma_f32 v88, v180, v244, v88
	v_fma_f32 v89, v181, v82, v89
	v_fma_f32 v90, v182, v245, v90
	v_fma_f32 v91, v183, v83, v91
	v_mul_f32_e32 v240, v240, v160
	v_mul_f32_e32 v92, v92, v161
	v_mul_f32_e32 v241, v241, v162
	v_mul_f32_e32 v93, v93, v163
	v_mul_f32_e32 v242, v242, v164
	v_mul_f32_e32 v94, v94, v165
	v_mul_f32_e32 v243, v243, v166
	v_mul_f32_e32 v95, v95, v167
	v_fma_f32 v84, v44, v240, v84
	v_fma_f32 v85, v45, v92, v85
	v_fma_f32 v86, v46, v241, v86
	v_fma_f32 v87, v47, v93, v87
	v_fma_f32 v88, v40, v242, v88
	v_fma_f32 v89, v41, v94, v89
	v_fma_f32 v90, v42, v243, v90
	v_fma_f32 v91, v43, v95, v91
	v_add_u32_e32 v150, 0x120000, v145
	global_store_dwordx4 v150, v[84:87], s[4:5]
	global_store_dwordx4 v150, v[88:91], s[4:5] offset:16
	s_nop 1
	v_add_u32_e32 v148, 0xb0000, v144
	v_add_u32_e32 v149, 0x160000, v145
	global_load_dwordx4 v[112:115], v148, s[90:91]
	global_load_dwordx4 v[116:119], v149, s[4:5]
	global_load_dwordx4 v[120:123], v149, s[4:5] offset:16
	global_load_dwordx4 v[124:127], v148, s[10:11]
	v_mul_f32_e32 v36, 0xbfb8aa3b, v36
	v_mul_f32_e32 v37, 0xbfb8aa3b, v37
	v_mul_f32_e32 v38, 0xbfb8aa3b, v38
	v_mul_f32_e32 v39, 0xbfb8aa3b, v39
	v_mul_f32_e32 v32, 0xbfb8aa3b, v32
	v_mul_f32_e32 v33, 0xbfb8aa3b, v33
	v_mul_f32_e32 v34, 0xbfb8aa3b, v34
	v_mul_f32_e32 v35, 0xbfb8aa3b, v35
	v_exp_f32_e32 v36, v36
	v_exp_f32_e32 v37, v37
	v_exp_f32_e32 v38, v38
	v_exp_f32_e32 v39, v39
	v_exp_f32_e32 v32, v32
	v_exp_f32_e32 v33, v33
	v_exp_f32_e32 v34, v34
	v_exp_f32_e32 v35, v35
	v_add_f32_e32 v36, 1.0, v36
	v_add_f32_e32 v37, 1.0, v37
	v_add_f32_e32 v38, 1.0, v38
	v_add_f32_e32 v39, 1.0, v39
	v_add_f32_e32 v32, 1.0, v32
	v_add_f32_e32 v33, 1.0, v33
	v_add_f32_e32 v34, 1.0, v34
	v_add_f32_e32 v35, 1.0, v35
	v_rcp_f32_e32 v36, v36
	v_rcp_f32_e32 v37, v37
	v_rcp_f32_e32 v38, v38
	v_rcp_f32_e32 v39, v39
	v_rcp_f32_e32 v32, v32
	v_rcp_f32_e32 v33, v33
	v_rcp_f32_e32 v34, v34
	v_rcp_f32_e32 v35, v35
	s_waitcnt vmcnt(18)
; __device__ __forceinline__ float bf_lo(unsigned w) { return __uint_as_float(w << 16); }
; __device__ __forceinline__ float bf_hi(unsigned w) { return __uint_as_float(w & 0xffff0000u); }
; __device__ __forceinline__ void load8(const bf16_t* src, float* v) { const u32x4 w = *(const u32x4*)src; v[0] = bf_lo(w.x); v[1] = bf_hi(w.x); v[2] = bf_lo(w.y); v[3] = bf_hi(w.y); v[4] = bf_lo(w.z); v[5] = bf_hi(w.z); v[6] = bf_lo(w.w); v[7] = bf_hi(w.w); }
; __device__ __forceinline__ float sigmoidf_(float v) { return __builtin_amdgcn_rcpf(1.f + __builtin_amdgcn_exp2f(-v * LOG2E)); }
;     __device__ __forceinline__ void operator()(const pg8::f32x4 (&acc)[2][2][4][2], const pg8::Unit& u, int wr, int wc, int fr, int fq) const {
;     ...
;                     } else if constexpr (KIND == EK_FIN) {
;                         const int c = pn * 256 + cl; const size_t off = (size_t)row * 2048 + c; float e[8]; load8(a.g0 + off, e);
;                         const f32x4 x0 = *(const f32x4*)(a.outf + off), x1 = *(const f32x4*)(a.outf + off + 4);
;                         const f32x4 g0 = *(const f32x4*)(a.gv + c), g1 = *(const f32x4*)(a.gv + c + 4);
;                         f32x4 r0, r1;
; #pragma unroll
;                         for (int j = 0; j < 4; ++j) { r0[j] = x0[j] + sigmoidf_(v[j]) * (e[j] * rs * g0[j]); r1[j] = x1[j] + sigmoidf_(v[4 + j]) * (e[4 + j] * rs * g1[j]); }
;                         *(f32x4*)(a.outf + off) = r0; *(f32x4*)(a.outf + off + 4) = r1;
; __global__ void __launch_bounds__(512, 2) fwd(Params P) {
;     ...
;             const float rsd = __builtin_amdgcn_rsqf(ssq_d[m] * (1.f / DM) + EPS);
;             const u32x2* dr = (const u32x2*)(DN + (size_t)m * DM) + lane;
;             f32x4* orow = (f32x4*)(OUT_P + (size_t)m * DM) + lane; u32x2* o = (u32x2*)(XN + (size_t)m * DM) + lane;
; #pragma unroll
;             for (int j = 0; j < 8; ++j) { const f32x4 xv = __builtin_nontemporal_load(&orow[64 * j]); const u32x2 dw = __builtin_nontemporal_load(&dr[64 * j]); const f32x4 g = g1[64 * j];
;                 f32x4 t; t.x = xv.x + bf_lo(dw.x) * rsd * g.x; t.y = xv.y + bf_hi(dw.x) * rsd * g.y; t.z = xv.z + bf_lo(dw.y) * rsd * g.z; t.w = xv.w + bf_hi(dw.y) * rsd * g.w;
	v_lshlrev_b32_e32 v151, 16, v224
	v_and_b32_e32 v224, 0xffff0000, v224
	v_lshlrev_b32_e32 v159, 16, v225
	v_and_b32_e32 v225, 0xffff0000, v225
	v_lshlrev_b32_e32 v244, 16, v226
	v_and_b32_e32 v226, 0xffff0000, v226
	v_lshlrev_b32_e32 v245, 16, v227
	v_and_b32_e32 v227, 0xffff0000, v227
	v_lshlrev_b32_e32 v240, 16, v236
	v_and_b32_e32 v236, 0xffff0000, v236
	v_lshlrev_b32_e32 v241, 16, v237
	v_and_b32_e32 v237, 0xffff0000, v237
	v_lshlrev_b32_e32 v242, 16, v238
	v_and_b32_e32 v238, 0xffff0000, v238
	v_lshlrev_b32_e32 v243, 16, v239
	v_and_b32_e32 v239, 0xffff0000, v239
	v_mul_f32_e32 v151, v205, v151
	v_mul_f32_e32 v224, v205, v224
	v_mul_f32_e32 v159, v205, v159
	v_mul_f32_e32 v225, v205, v225
	v_mul_f32_e32 v244, v205, v244
	v_mul_f32_e32 v226, v205, v226
	v_mul_f32_e32 v245, v205, v245
	v_mul_f32_e32 v227, v205, v227
	v_mul_f32_e32 v240, v197, v240
	v_mul_f32_e32 v236, v197, v236
	v_mul_f32_e32 v241, v197, v241
	v_mul_f32_e32 v237, v197, v237
	v_mul_f32_e32 v242, v197, v242
	v_mul_f32_e32 v238, v197, v238
	v_mul_f32_e32 v243, v197, v243
	v_mul_f32_e32 v239, v197, v239
	v_fma_f32 v228, v184, v151, v228
	v_fma_f32 v229, v185, v224, v229
	v_fma_f32 v230, v186, v159, v230
	v_fma_f32 v231, v187, v225, v231
	v_fma_f32 v232, v188, v244, v232
	v_fma_f32 v233, v189, v226, v233
	v_fma_f32 v234, v190, v245, v234
	v_fma_f32 v235, v191, v227, v235
	v_mul_f32_e32 v240, v240, v168
	v_mul_f32_e32 v236, v236, v169
	v_mul_f32_e32 v241, v241, v170
	v_mul_f32_e32 v237, v237, v171
	v_mul_f32_e32 v242, v242, v172
	v_mul_f32_e32 v238, v238, v173
	v_mul_f32_e32 v243, v243, v174
	v_mul_f32_e32 v239, v239, v175
	v_fma_f32 v228, v36, v240, v228
	v_fma_f32 v229, v37, v236, v229
	v_fma_f32 v230, v38, v241, v230
	v_fma_f32 v231, v39, v237, v231
	v_fma_f32 v232, v32, v242, v232
	v_fma_f32 v233, v33, v238, v233
	v_fma_f32 v234, v34, v243, v234
	v_fma_f32 v235, v35, v239, v235
	global_store_dwordx4 v150, v[228:231], s[4:5] offset:512
	global_store_dwordx4 v150, v[232:235], s[4:5] offset:528
	s_nop 1
	global_load_dwordx4 v[208:211], v148, s[90:91] offset:256
	global_load_dwordx4 v[212:215], v149, s[4:5] offset:512
	global_load_dwordx4 v[216:219], v149, s[4:5] offset:528
	global_load_dwordx4 v[220:223], v148, s[10:11] offset:256
	v_mul_f32_e32 v28, 0xbfb8aa3b, v28
	v_mul_f32_e32 v29, 0xbfb8aa3b, v29
	v_mul_f32_e32 v30, 0xbfb8aa3b, v30
	v_mul_f32_e32 v31, 0xbfb8aa3b, v31
	v_mul_f32_e32 v24, 0xbfb8aa3b, v24
	v_mul_f32_e32 v25, 0xbfb8aa3b, v25
	v_mul_f32_e32 v26, 0xbfb8aa3b, v26
	v_mul_f32_e32 v27, 0xbfb8aa3b, v27
	v_exp_f32_e32 v28, v28
	v_exp_f32_e32 v29, v29
	v_exp_f32_e32 v30, v30
	v_exp_f32_e32 v31, v31
	v_exp_f32_e32 v24, v24
	v_exp_f32_e32 v25, v25
	v_exp_f32_e32 v26, v26
	v_exp_f32_e32 v27, v27
	v_add_f32_e32 v28, 1.0, v28
	v_add_f32_e32 v29, 1.0, v29
	v_add_f32_e32 v30, 1.0, v30
	v_add_f32_e32 v31, 1.0, v31
	v_add_f32_e32 v24, 1.0, v24
	v_add_f32_e32 v25, 1.0, v25
	v_add_f32_e32 v26, 1.0, v26
	v_add_f32_e32 v27, 1.0, v27
	v_rcp_f32_e32 v28, v28
	v_rcp_f32_e32 v29, v29
	v_rcp_f32_e32 v30, v30
	v_rcp_f32_e32 v31, v31
	v_rcp_f32_e32 v24, v24
	v_rcp_f32_e32 v25, v25
	v_rcp_f32_e32 v26, v26
	v_rcp_f32_e32 v27, v27
	s_waitcnt vmcnt(18)
	v_fmamk_f32 v198, v198, 0x3a000000, v158
	v_fmamk_f32 v206, v206, 0x3a000000, v158
	v_rsq_f32_e32 v198, v198
	v_rsq_f32_e32 v206, v206
	v_lshlrev_b32_e32 v151, 16, v96
	v_and_b32_e32 v96, 0xffff0000, v96
	v_lshlrev_b32_e32 v159, 16, v97
	v_and_b32_e32 v97, 0xffff0000, v97
	v_lshlrev_b32_e32 v244, 16, v98
	v_and_b32_e32 v98, 0xffff0000, v98
	v_lshlrev_b32_e32 v245, 16, v99
	v_and_b32_e32 v99, 0xffff0000, v99
	v_lshlrev_b32_e32 v240, 16, v108
	v_and_b32_e32 v108, 0xffff0000, v108
	v_lshlrev_b32_e32 v241, 16, v109
	v_and_b32_e32 v109, 0xffff0000, v109
	v_lshlrev_b32_e32 v242, 16, v110
	v_and_b32_e32 v110, 0xffff0000, v110
	v_lshlrev_b32_e32 v243, 16, v111
	v_and_b32_e32 v111, 0xffff0000, v111
	v_mul_f32_e32 v151, v206, v151
	v_mul_f32_e32 v96, v206, v96
	v_mul_f32_e32 v159, v206, v159
	v_mul_f32_e32 v97, v206, v97
	v_mul_f32_e32 v244, v206, v244
	v_mul_f32_e32 v98, v206, v98
	v_mul_f32_e32 v245, v206, v245
	v_mul_f32_e32 v99, v206, v99
	v_mul_f32_e32 v240, v198, v240
	v_mul_f32_e32 v108, v198, v108
	v_mul_f32_e32 v241, v198, v241
	v_mul_f32_e32 v109, v198, v109
	v_mul_f32_e32 v242, v198, v242
	v_mul_f32_e32 v110, v198, v110
	v_mul_f32_e32 v243, v198, v243
	v_mul_f32_e32 v111, v198, v111
	v_fma_f32 v100, v176, v151, v100
	v_fma_f32 v101, v177, v96, v101
	v_fma_f32 v102, v178, v159, v102
	v_fma_f32 v103, v179, v97, v103
	v_fma_f32 v104, v180, v244, v104
	v_fma_f32 v105, v181, v98, v105
	v_fma_f32 v106, v182, v245, v106
	v_fma_f32 v107, v183, v99, v107
	v_mul_f32_e32 v240, v240, v160
	v_mul_f32_e32 v108, v108, v161
	v_mul_f32_e32 v241, v241, v162
	v_mul_f32_e32 v109, v109, v163
	v_mul_f32_e32 v242, v242, v164
	v_mul_f32_e32 v110, v110, v165
	v_mul_f32_e32 v243, v243, v166
	v_mul_f32_e32 v111, v111, v167
	v_fma_f32 v100, v28, v240, v100
	v_fma_f32 v101, v29, v108, v101
	v_fma_f32 v102, v30, v241, v102
	v_fma_f32 v103, v31, v109, v103
	v_fma_f32 v104, v24, v242, v104
	v_fma_f32 v105, v25, v110, v105
	v_fma_f32 v106, v26, v243, v106
	v_fma_f32 v107, v27, v111, v107
	v_add_u32_e32 v150, 0x140000, v145
	global_store_dwordx4 v150, v[100:103], s[4:5]
	global_store_dwordx4 v150, v[104:107], s[4:5] offset:16
	v_mul_f32_e32 v20, 0xbfb8aa3b, v20
	v_mul_f32_e32 v21, 0xbfb8aa3b, v21
	v_mul_f32_e32 v22, 0xbfb8aa3b, v22
	v_mul_f32_e32 v23, 0xbfb8aa3b, v23
	v_mul_f32_e32 v16, 0xbfb8aa3b, v16
	v_mul_f32_e32 v17, 0xbfb8aa3b, v17
	v_mul_f32_e32 v18, 0xbfb8aa3b, v18
	v_mul_f32_e32 v19, 0xbfb8aa3b, v19
	v_exp_f32_e32 v20, v20
	v_exp_f32_e32 v21, v21
	v_exp_f32_e32 v22, v22
	v_exp_f32_e32 v23, v23
	v_exp_f32_e32 v16, v16
	v_exp_f32_e32 v17, v17
	v_exp_f32_e32 v18, v18
	v_exp_f32_e32 v19, v19
	v_add_f32_e32 v20, 1.0, v20
	v_add_f32_e32 v21, 1.0, v21
	v_add_f32_e32 v22, 1.0, v22
	v_add_f32_e32 v23, 1.0, v23
	v_add_f32_e32 v16, 1.0, v16
	v_add_f32_e32 v17, 1.0, v17
	v_add_f32_e32 v18, 1.0, v18
	v_add_f32_e32 v19, 1.0, v19
	v_rcp_f32_e32 v20, v20
	v_rcp_f32_e32 v21, v21
	v_rcp_f32_e32 v22, v22
	v_rcp_f32_e32 v23, v23
	v_rcp_f32_e32 v16, v16
	v_rcp_f32_e32 v17, v17
	v_rcp_f32_e32 v18, v18
	v_rcp_f32_e32 v19, v19
	s_waitcnt vmcnt(14)
; __device__ __forceinline__ float bf_lo(unsigned w) { return __uint_as_float(w << 16); }
; __device__ __forceinline__ float bf_hi(unsigned w) { return __uint_as_float(w & 0xffff0000u); }
; __device__ __forceinline__ void load8(const bf16_t* src, float* v) { const u32x4 w = *(const u32x4*)src; v[0] = bf_lo(w.x); v[1] = bf_hi(w.x); v[2] = bf_lo(w.y); v[3] = bf_hi(w.y); v[4] = bf_lo(w.z); v[5] = bf_hi(w.z); v[6] = bf_lo(w.w); v[7] = bf_hi(w.w); }
; __device__ __forceinline__ float sigmoidf_(float v) { return __builtin_amdgcn_rcpf(1.f + __builtin_amdgcn_exp2f(-v * LOG2E)); }
;     __device__ __forceinline__ void operator()(const pg8::f32x4 (&acc)[2][2][4][2], const pg8::Unit& u, int wr, int wc, int fr, int fq) const {
;     ...
;                     } else if constexpr (KIND == EK_FIN) {
;                         const int c = pn * 256 + cl; const size_t off = (size_t)row * 2048 + c; float e[8]; load8(a.g0 + off, e);
;                         const f32x4 x0 = *(const f32x4*)(a.outf + off), x1 = *(const f32x4*)(a.outf + off + 4);
;                         const f32x4 g0 = *(const f32x4*)(a.gv + c), g1 = *(const f32x4*)(a.gv + c + 4);
;                         f32x4 r0, r1;
; #pragma unroll
;                         for (int j = 0; j < 4; ++j) { r0[j] = x0[j] + sigmoidf_(v[j]) * (e[j] * rs * g0[j]); r1[j] = x1[j] + sigmoidf_(v[4 + j]) * (e[4 + j] * rs * g1[j]); }
;                         *(f32x4*)(a.outf + off) = r0; *(f32x4*)(a.outf + off + 4) = r1;
; __global__ void __launch_bounds__(512, 2) fwd(Params P) {
;     ...
;             const float rsd = __builtin_amdgcn_rsqf(ssq_d[m] * (1.f / DM) + EPS);
;             const u32x2* dr = (const u32x2*)(DN + (size_t)m * DM) + lane;
;             f32x4* orow = (f32x4*)(OUT_P + (size_t)m * DM) + lane; u32x2* o = (u32x2*)(XN + (size_t)m * DM) + lane;
; #pragma unroll
;             for (int j = 0; j < 8; ++j) { const f32x4 xv = __builtin_nontemporal_load(&orow[64 * j]); const u32x2 dw = __builtin_nontemporal_load(&dr[64 * j]); const f32x4 g = g1[64 * j];
;                 f32x4 t; t.x = xv.x + bf_lo(dw.x) * rsd * g.x; t.y = xv.y + bf_hi(dw.x) * rsd * g.y; t.z = xv.z + bf_lo(dw.y) * rsd * g.z; t.w = xv.w + bf_hi(dw.y) * rsd * g.w;
	v_lshlrev_b32_e32 v151, 16, v64
	v_and_b32_e32 v64, 0xffff0000, v64
	v_lshlrev_b32_e32 v159, 16, v65
	v_and_b32_e32 v65, 0xffff0000, v65
	v_lshlrev_b32_e32 v244, 16, v66
	v_and_b32_e32 v66, 0xffff0000, v66
	v_lshlrev_b32_e32 v245, 16, v67
	v_and_b32_e32 v67, 0xffff0000, v67
	v_lshlrev_b32_e32 v240, 16, v76
	v_and_b32_e32 v76, 0xffff0000, v76
	v_lshlrev_b32_e32 v241, 16, v77
	v_and_b32_e32 v77, 0xffff0000, v77
	v_lshlrev_b32_e32 v242, 16, v78
	v_and_b32_e32 v78, 0xffff0000, v78
	v_lshlrev_b32_e32 v243, 16, v79
	v_and_b32_e32 v79, 0xffff0000, v79
	v_mul_f32_e32 v151, v206, v151
	v_mul_f32_e32 v64, v206, v64
	v_mul_f32_e32 v159, v206, v159
	v_mul_f32_e32 v65, v206, v65
	v_mul_f32_e32 v244, v206, v244
	v_mul_f32_e32 v66, v206, v66
	v_mul_f32_e32 v245, v206, v245
	v_mul_f32_e32 v67, v206, v67
	v_mul_f32_e32 v240, v198, v240
	v_mul_f32_e32 v76, v198, v76
	v_mul_f32_e32 v241, v198, v241
	v_mul_f32_e32 v77, v198, v77
	v_mul_f32_e32 v242, v198, v242
	v_mul_f32_e32 v78, v198, v78
	v_mul_f32_e32 v243, v198, v243
	v_mul_f32_e32 v79, v198, v79
	v_fma_f32 v68, v184, v151, v68
	v_fma_f32 v69, v185, v64, v69
	v_fma_f32 v70, v186, v159, v70
	v_fma_f32 v71, v187, v65, v71
	v_fma_f32 v72, v188, v244, v72
	v_fma_f32 v73, v189, v66, v73
	v_fma_f32 v74, v190, v245, v74
	v_fma_f32 v75, v191, v67, v75
	v_mul_f32_e32 v240, v240, v168
	v_mul_f32_e32 v76, v76, v169
	v_mul_f32_e32 v241, v241, v170
	v_mul_f32_e32 v77, v77, v171
	v_mul_f32_e32 v242, v242, v172
	v_mul_f32_e32 v78, v78, v173
	v_mul_f32_e32 v243, v243, v174
	v_mul_f32_e32 v79, v79, v175
	v_fma_f32 v68, v20, v240, v68
	v_fma_f32 v69, v21, v76, v69
	v_fma_f32 v70, v22, v241, v70
	v_fma_f32 v71, v23, v77, v71
	v_fma_f32 v72, v16, v242, v72
	v_fma_f32 v73, v17, v78, v73
	v_fma_f32 v74, v18, v243, v74
	v_fma_f32 v75, v19, v79, v75
	global_store_dwordx4 v150, v[68:71], s[4:5] offset:512
	global_store_dwordx4 v150, v[72:75], s[4:5] offset:528
	v_mul_f32_e32 v12, 0xbfb8aa3b, v12
	v_mul_f32_e32 v13, 0xbfb8aa3b, v13
	v_mul_f32_e32 v14, 0xbfb8aa3b, v14
	v_mul_f32_e32 v15, 0xbfb8aa3b, v15
	v_mul_f32_e32 v8, 0xbfb8aa3b, v8
	v_mul_f32_e32 v9, 0xbfb8aa3b, v9
	v_mul_f32_e32 v10, 0xbfb8aa3b, v10
	v_mul_f32_e32 v11, 0xbfb8aa3b, v11
	v_exp_f32_e32 v12, v12
	v_exp_f32_e32 v13, v13
	v_exp_f32_e32 v14, v14
	v_exp_f32_e32 v15, v15
	v_exp_f32_e32 v8, v8
	v_exp_f32_e32 v9, v9
	v_exp_f32_e32 v10, v10
	v_exp_f32_e32 v11, v11
	v_add_f32_e32 v12, 1.0, v12
	v_add_f32_e32 v13, 1.0, v13
	v_add_f32_e32 v14, 1.0, v14
	v_add_f32_e32 v15, 1.0, v15
	v_add_f32_e32 v8, 1.0, v8
	v_add_f32_e32 v9, 1.0, v9
	v_add_f32_e32 v10, 1.0, v10
	v_add_f32_e32 v11, 1.0, v11
	v_rcp_f32_e32 v12, v12
	v_rcp_f32_e32 v13, v13
	v_rcp_f32_e32 v14, v14
	v_rcp_f32_e32 v15, v15
	v_rcp_f32_e32 v8, v8
	v_rcp_f32_e32 v9, v9
	v_rcp_f32_e32 v10, v10
	v_rcp_f32_e32 v11, v11
	s_waitcnt vmcnt(10)
; __device__ __forceinline__ float bf_lo(unsigned w) { return __uint_as_float(w << 16); }
; __device__ __forceinline__ float bf_hi(unsigned w) { return __uint_as_float(w & 0xffff0000u); }
; __device__ __forceinline__ void load8(const bf16_t* src, float* v) { const u32x4 w = *(const u32x4*)src; v[0] = bf_lo(w.x); v[1] = bf_hi(w.x); v[2] = bf_lo(w.y); v[3] = bf_hi(w.y); v[4] = bf_lo(w.z); v[5] = bf_hi(w.z); v[6] = bf_lo(w.w); v[7] = bf_hi(w.w); }
; __device__ __forceinline__ float sigmoidf_(float v) { return __builtin_amdgcn_rcpf(1.f + __builtin_amdgcn_exp2f(-v * LOG2E)); }
;     __device__ __forceinline__ void operator()(const pg8::f32x4 (&acc)[2][2][4][2], const pg8::Unit& u, int wr, int wc, int fr, int fq) const {
;     ...
;                     } else if constexpr (KIND == EK_FIN) {
;                         const int c = pn * 256 + cl; const size_t off = (size_t)row * 2048 + c; float e[8]; load8(a.g0 + off, e);
;                         const f32x4 x0 = *(const f32x4*)(a.outf + off), x1 = *(const f32x4*)(a.outf + off + 4);
;                         const f32x4 g0 = *(const f32x4*)(a.gv + c), g1 = *(const f32x4*)(a.gv + c + 4);
;                         f32x4 r0, r1;
; #pragma unroll
;                         for (int j = 0; j < 4; ++j) { r0[j] = x0[j] + sigmoidf_(v[j]) * (e[j] * rs * g0[j]); r1[j] = x1[j] + sigmoidf_(v[4 + j]) * (e[4 + j] * rs * g1[j]); }
;                         *(f32x4*)(a.outf + off) = r0; *(f32x4*)(a.outf + off + 4) = r1;
; __global__ void __launch_bounds__(512, 2) fwd(Params P) {
;     ...
;             const float rsd = __builtin_amdgcn_rsqf(ssq_d[m] * (1.f / DM) + EPS);
;             const u32x2* dr = (const u32x2*)(DN + (size_t)m * DM) + lane;
;             f32x4* orow = (f32x4*)(OUT_P + (size_t)m * DM) + lane; u32x2* o = (u32x2*)(XN + (size_t)m * DM) + lane;
; #pragma unroll
;             for (int j = 0; j < 8; ++j) { const f32x4 xv = __builtin_nontemporal_load(&orow[64 * j]); const u32x2 dw = __builtin_nontemporal_load(&dr[64 * j]); const f32x4 g = g1[64 * j];
;                 f32x4 t; t.x = xv.x + bf_lo(dw.x) * rsd * g.x; t.y = xv.y + bf_hi(dw.x) * rsd * g.y; t.z = xv.z + bf_lo(dw.y) * rsd * g.z; t.w = xv.w + bf_hi(dw.y) * rsd * g.w;
	v_fmamk_f32 v199, v199, 0x3a000000, v158
	v_fmamk_f32 v207, v207, 0x3a000000, v158
	v_rsq_f32_e32 v199, v199
	v_rsq_f32_e32 v207, v207
	v_lshlrev_b32_e32 v151, 16, v112
	v_and_b32_e32 v112, 0xffff0000, v112
	v_lshlrev_b32_e32 v159, 16, v113
	v_and_b32_e32 v113, 0xffff0000, v113
	v_lshlrev_b32_e32 v244, 16, v114
	v_and_b32_e32 v114, 0xffff0000, v114
	v_lshlrev_b32_e32 v245, 16, v115
	v_and_b32_e32 v115, 0xffff0000, v115
	v_lshlrev_b32_e32 v240, 16, v124
	v_and_b32_e32 v124, 0xffff0000, v124
	v_lshlrev_b32_e32 v241, 16, v125
	v_and_b32_e32 v125, 0xffff0000, v125
	v_lshlrev_b32_e32 v242, 16, v126
	v_and_b32_e32 v126, 0xffff0000, v126
	v_lshlrev_b32_e32 v243, 16, v127
	v_and_b32_e32 v127, 0xffff0000, v127
	v_mul_f32_e32 v151, v207, v151
	v_mul_f32_e32 v112, v207, v112
	v_mul_f32_e32 v159, v207, v159
	v_mul_f32_e32 v113, v207, v113
	v_mul_f32_e32 v244, v207, v244
	v_mul_f32_e32 v114, v207, v114
	v_mul_f32_e32 v245, v207, v245
	v_mul_f32_e32 v115, v207, v115
	v_mul_f32_e32 v240, v199, v240
	v_mul_f32_e32 v124, v199, v124
	v_mul_f32_e32 v241, v199, v241
	v_mul_f32_e32 v125, v199, v125
	v_mul_f32_e32 v242, v199, v242
	v_mul_f32_e32 v126, v199, v126
	v_mul_f32_e32 v243, v199, v243
	v_mul_f32_e32 v127, v199, v127
	v_fma_f32 v116, v176, v151, v116
	v_fma_f32 v117, v177, v112, v117
	v_fma_f32 v118, v178, v159, v118
	v_fma_f32 v119, v179, v113, v119
	v_fma_f32 v120, v180, v244, v120
	v_fma_f32 v121, v181, v114, v121
	v_fma_f32 v122, v182, v245, v122
	v_fma_f32 v123, v183, v115, v123
	v_mul_f32_e32 v240, v240, v160
	v_mul_f32_e32 v124, v124, v161
	v_mul_f32_e32 v241, v241, v162
	v_mul_f32_e32 v125, v125, v163
	v_mul_f32_e32 v242, v242, v164
	v_mul_f32_e32 v126, v126, v165
	v_mul_f32_e32 v243, v243, v166
	v_mul_f32_e32 v127, v127, v167
	v_fma_f32 v116, v12, v240, v116
	v_fma_f32 v117, v13, v124, v117
	v_fma_f32 v118, v14, v241, v118
	v_fma_f32 v119, v15, v125, v119
	v_fma_f32 v120, v8, v242, v120
	v_fma_f32 v121, v9, v126, v121
	v_fma_f32 v122, v10, v243, v122
	v_fma_f32 v123, v11, v127, v123
	v_add_u32_e32 v150, 0x160000, v145
	global_store_dwordx4 v150, v[116:119], s[4:5]
	global_store_dwordx4 v150, v[120:123], s[4:5] offset:16
	v_mul_f32_e32 v4, 0xbfb8aa3b, v4
	v_mul_f32_e32 v5, 0xbfb8aa3b, v5
	v_mul_f32_e32 v6, 0xbfb8aa3b, v6
	v_mul_f32_e32 v7, 0xbfb8aa3b, v7
	v_mul_f32_e32 v0, 0xbfb8aa3b, v0
	v_mul_f32_e32 v1, 0xbfb8aa3b, v1
	v_mul_f32_e32 v2, 0xbfb8aa3b, v2
	v_mul_f32_e32 v3, 0xbfb8aa3b, v3
	v_exp_f32_e32 v4, v4
	v_exp_f32_e32 v5, v5
	v_exp_f32_e32 v6, v6
	v_exp_f32_e32 v7, v7
	v_exp_f32_e32 v0, v0
	v_exp_f32_e32 v1, v1
	v_exp_f32_e32 v2, v2
	v_exp_f32_e32 v3, v3
	v_add_f32_e32 v4, 1.0, v4
	v_add_f32_e32 v5, 1.0, v5
	v_add_f32_e32 v6, 1.0, v6
	v_add_f32_e32 v7, 1.0, v7
	v_add_f32_e32 v0, 1.0, v0
	v_add_f32_e32 v1, 1.0, v1
	v_add_f32_e32 v2, 1.0, v2
	v_add_f32_e32 v3, 1.0, v3
	v_rcp_f32_e32 v4, v4
	v_rcp_f32_e32 v5, v5
	v_rcp_f32_e32 v6, v6
	v_rcp_f32_e32 v7, v7
	v_rcp_f32_e32 v0, v0
	v_rcp_f32_e32 v1, v1
	v_rcp_f32_e32 v2, v2
	v_rcp_f32_e32 v3, v3
	s_waitcnt vmcnt(6)
	v_lshlrev_b32_e32 v151, 16, v208
	v_and_b32_e32 v208, 0xffff0000, v208
	v_lshlrev_b32_e32 v159, 16, v209
	v_and_b32_e32 v209, 0xffff0000, v209
	v_lshlrev_b32_e32 v244, 16, v210
	v_and_b32_e32 v210, 0xffff0000, v210
	v_lshlrev_b32_e32 v245, 16, v211
	v_and_b32_e32 v211, 0xffff0000, v211
	v_lshlrev_b32_e32 v240, 16, v220
	v_and_b32_e32 v220, 0xffff0000, v220
	v_lshlrev_b32_e32 v241, 16, v221
	v_and_b32_e32 v221, 0xffff0000, v221
	v_lshlrev_b32_e32 v242, 16, v222
	v_and_b32_e32 v222, 0xffff0000, v222
	v_lshlrev_b32_e32 v243, 16, v223
	v_and_b32_e32 v223, 0xffff0000, v223
	v_mul_f32_e32 v151, v207, v151
	v_mul_f32_e32 v208, v207, v208
	v_mul_f32_e32 v159, v207, v159
	v_mul_f32_e32 v209, v207, v209
	v_mul_f32_e32 v244, v207, v244
	v_mul_f32_e32 v210, v207, v210
	v_mul_f32_e32 v245, v207, v245
	v_mul_f32_e32 v211, v207, v211
	v_mul_f32_e32 v240, v199, v240
	v_mul_f32_e32 v220, v199, v220
	v_mul_f32_e32 v241, v199, v241
	v_mul_f32_e32 v221, v199, v221
	v_mul_f32_e32 v242, v199, v242
	v_mul_f32_e32 v222, v199, v222
	v_mul_f32_e32 v243, v199, v243
	v_mul_f32_e32 v223, v199, v223
	v_fma_f32 v212, v184, v151, v212
	v_fma_f32 v213, v185, v208, v213
	v_fma_f32 v214, v186, v159, v214
	v_fma_f32 v215, v187, v209, v215
	v_fma_f32 v216, v188, v244, v216
	v_fma_f32 v217, v189, v210, v217
	v_fma_f32 v218, v190, v245, v218
	v_fma_f32 v219, v191, v211, v219
	v_mul_f32_e32 v240, v240, v168
	v_mul_f32_e32 v220, v220, v169
	v_mul_f32_e32 v241, v241, v170
	v_mul_f32_e32 v221, v221, v171
	v_mul_f32_e32 v242, v242, v172
	v_mul_f32_e32 v222, v222, v173
	v_mul_f32_e32 v243, v243, v174
	v_mul_f32_e32 v223, v223, v175
	v_fma_f32 v212, v4, v240, v212
	v_fma_f32 v213, v5, v220, v213
	v_fma_f32 v214, v6, v241, v214
	v_fma_f32 v215, v7, v221, v215
	v_fma_f32 v216, v0, v242, v216
	v_fma_f32 v217, v1, v222, v217
	v_fma_f32 v218, v2, v243, v218
	v_fma_f32 v219, v3, v223, v219
	global_store_dwordx4 v150, v[212:215], s[4:5] offset:512
	global_store_dwordx4 v150, v[216:219], s[4:5] offset:528
	s_andn2_b64 vcc, exec, s[0:1]
	s_mov_b64 s[0:1], -1
	s_cbranch_vccnz .LBB0_1554
	s_andn2_b64 vcc, exec, s[8:9]
	s_cbranch_vccnz .LBB0_1553
	s_barrier
	s_branch .LBB0_1553
